# attention: 512-row ring with one barrier per block, next block's Q and K/V rows loaded during the key loop, explicit max subtraction
# speedup vs baseline: 1.0288x; 1.0010x over previous
.LBB0_327:
	s_andn2_b64 vcc, exec, s[4:5]
	s_cbranch_vccnz .LBB0_800
	s_cmp_lt_i32 s96, 1
	s_mov_b64 s[4:5], -1
	s_cbranch_scc1 .LBB0_384
	s_cmp_eq_u32 s96, 1
	s_cbranch_scc0 .LBB0_383
	v_readlane_b32 s4, v253, 18
	v_mov_b32_e32 v1, v175
	v_readlane_b32 s5, v253, 19
	s_andn2_b64 vcc, exec, s[4:5]
	v_readfirstlane_b32 s3, v1
	s_cbranch_vccnz .LBB0_383
	v_writelane_b32 v255, s96, 7
	v_writelane_b32 v255, s97, 8
	v_writelane_b32 v255, s98, 9
	v_writelane_b32 v255, s99, 10
	v_writelane_b32 v255, s86, 0
	v_writelane_b32 v255, s87, 1
	v_writelane_b32 v255, s42, 11
	s_mov_b32 s5, 0
	v_lshrrev_b32_e32 v212, 6, v175
	s_lshl_b32 s4, s42, 8
	v_writelane_b32 v255, s5, 12
	v_readfirstlane_b32 s3, v212
	v_readlane_b32 s48, v254, 20
	v_readlane_b32 s49, v254, 21
	v_readlane_b32 s46, v254, 22
	v_readlane_b32 s47, v254, 23
	v_readlane_b32 s50, v254, 12
	v_readlane_b32 s51, v254, 13
	v_readlane_b32 s59, v253, 3
	s_mov_b32 s52, s31
	s_nop 3
	s_add_u32 s48, s48, s4
	s_addc_u32 s49, s49, 0
	s_add_u32 s46, s46, s4
	s_addc_u32 s47, s47, 0
	s_lshr_b32 s4, s4, 2
	s_add_u32 s50, s50, s4
	s_addc_u32 s51, s51, 0
	s_add_u32 s42, s36, 0x180000
	s_addc_u32 s43, s37, 0
	s_lshr_b32 s71, s3, 1
	s_and_b32 s70, s3, 1
	s_lshl_b32 s70, s70, 6
	s_movk_i32 s60, 0xc00
	v_and_b32_e32 v1, 31, v175
	v_bfe_u32 v2, v175, 5, 1
	v_lshlrev_b32_e32 v250, 2, v2
	v_sub_u32_e32 v15, v1, v250
	v_cmp_eq_u32_e64 s[66:67], 1, v2
	v_and_b32_e32 v212, 7, v175
	v_cmp_gt_u32_e64 s[62:63], 2, v212
	v_cmp_eq_u32_e64 s[64:65], 0, v212
	v_lshlrev_b32_e32 v4, 4, v212
	v_lshrrev_b32_e32 v172, 3, v175
	v_mov_b32_e32 v216, 0x90
	v_mad_u32_u24 v5, v172, v216, v4
	v_add_u32_e32 v7, 0xffffff80, v172
	v_lshlrev_b32_e32 v172, 4, v2
	v_mad_u32_u24 v8, v1, v216, v172
	v_bfe_u32 v172, v175, 2, 2
	v_add_u32_e32 v172, v172, v250
	v_bfe_u32 v217, v175, 4, 1
	v_lshlrev_b32_e32 v217, 5, v217
	v_and_b32_e32 v250, 3, v175
	v_lshl_add_u32 v217, v250, 3, v217
	v_mad_u32_u24 v9, v172, v216, v217
	v_add_u32_e32 v9, 0x12000, v9
	v_add_u32_e32 v212, s70, v1
	s_lshl_b32 s4, s71, 7
	v_lshlrev_b32_e32 v172, 4, v2
	v_add_u32_e32 v172, s4, v172
	v_mul_u32_u24_e32 v216, 0xc00, v212
	v_add_u32_e32 v10, v216, v172
	v_add_u32_e32 v11, 0x18000, v10
	v_lshlrev_b32_e32 v12, 6, v212
	v_lshl_add_u32 v13, v212, 11, v172
	v_add_u32_e32 v14, 0x10000, v13
	s_cmpk_lt_i32 s52, 0x100
	s_cbranch_scc0 .Lat_exit
.Lat_chunk:
	s_and_b32 s54, s52, 3
	s_bfe_u32 s85, s52, 0x40002
	s_lshr_b32 s55, s52, 6
	s_lshl_b32 s53, s85, 2
	s_mov_b32 s58, 0
	s_lshl_b32 s4, s54, 2
	s_add_u32 s56, s4, s71
	s_lshl_b32 s6, s55, 13
	v_readlane_b32 s8, v254, 33
	v_readlane_b32 s9, v254, 34
	s_mul_i32 s10, s6, 0xc00
	s_lshl_b32 s13, s54, 7
	s_add_u32 s10, s10, s13
	s_nop 0
	s_add_u32 s38, s8, s10
	s_addc_u32 s39, s9, 0
	s_barrier
.Lat_unit:
	s_lshl_b32 s5, s56, 2
	s_load_dword s11, s[50:51], s5
	s_lshl_b32 s6, s55, 13
	s_lshl_b32 s7, s53, 7
	s_mul_i32 s10, s7, 0xc00
	s_lshl_b32 s13, s54, 9
	s_add_u32 s10, s10, s13
	s_lshl_b32 s13, s54, 7
	s_sub_u32 s10, s10, s13
	s_add_u32 s40, s38, s10
	s_addc_u32 s41, s39, 0
	s_add_u32 s86, s40, 0x60000
	s_addc_u32 s87, s41, 0
	s_lshl_b32 s10, s53, 13
	s_add_u32 s72, s42, s10
	s_addc_u32 s73, s43, 0
	v_readlane_b32 s8, v253, 20
	v_readlane_b32 s9, v253, 21
	s_add_u32 s10, s6, s7
	s_lshl_b32 s10, s10, 11
	s_lshl_b32 s13, s54, 9
	s_add_u32 s10, s10, s13
	s_add_u32 s44, s8, s10
	s_addc_u32 s45, s9, 0
	s_add_u32 s4, s53, 3
	s_and_b32 s4, s4, 3
	s_lshl_b32 s83, s4, 7
	s_cmp_eq_u32 s53, 0
	s_cselect_b32 s4, 128, 0
	s_sub_i32 s4, s4, s70
	s_max_i32 s4, s4, 0
	s_lshr_b32 s57, s4, 5
	s_movk_i32 s4, 0x100
	s_cmp_eq_u32 s53, 63
	s_cselect_b32 s4, s4, 0x180
	s_sub_u32 s4, s4, s70
	s_lshr_b32 s4, s4, 5
	s_min_u32 s68, s4, 10
	v_add_u32_e32 v217, s7, v7
	s_cmp_lg_u32 s58, 0
	s_cbranch_scc1 .Lat_incr_1
	global_load_dwordx4 v[192:195], v10, s[40:41] offset:0
	global_load_dwordx4 v[196:199], v10, s[40:41] offset:32
	global_load_dwordx4 v[200:203], v10, s[40:41] offset:64
	global_load_dwordx4 v[204:207], v10, s[40:41] offset:96
	global_load_dwordx4 v[234:237], v11, s[40:41] offset:0
	global_load_dwordx4 v[238:241], v11, s[40:41] offset:32
	global_load_dwordx4 v[242:245], v11, s[40:41] offset:64
	global_load_dwordx4 v[246:249], v11, s[40:41] offset:96
	v_lshlrev_b32_e32 v212, 1, v4
	global_load_dwordx4 v[48:51], v212, s[46:47]
	global_load_dwordx4 v[52:55], v212, s[46:47] offset:16
	v_add_u32_e32 v212, 0, v217
	v_max_i32_e32 v212, 0, v212
	v_min_u32_e32 v212, 0x1fff, v212
	v_mul_lo_u32 v172, v212, s60
	v_add_u32_e32 v172, v172, v4
	global_load_dwordx4 v[16:19], v172, s[38:39] offset:2048
	global_load_dwordx4 v[20:23], v172, s[38:39] offset:2560
	v_lshlrev_b32_e32 v216, 6, v212
	s_mov_b64 exec, s[62:63]
	global_load_dwordx4 v[80:83], v216, s[42:43] offset:0
	global_load_dwordx4 v[84:87], v216, s[42:43] offset:16
	global_load_dwordx4 v[88:91], v216, s[42:43] offset:32
	global_load_dwordx4 v[92:95], v216, s[42:43] offset:48
	s_mov_b64 exec, -1
	v_add_u32_e32 v212, 64, v217
	v_max_i32_e32 v212, 0, v212
	v_min_u32_e32 v212, 0x1fff, v212
	v_mul_lo_u32 v172, v212, s60
	v_add_u32_e32 v172, v172, v4
	global_load_dwordx4 v[24:27], v172, s[38:39] offset:2048
	global_load_dwordx4 v[28:31], v172, s[38:39] offset:2560
	v_lshlrev_b32_e32 v216, 6, v212
	s_mov_b64 exec, s[62:63]
	global_load_dwordx4 v[96:99], v216, s[42:43] offset:0
	global_load_dwordx4 v[100:103], v216, s[42:43] offset:16
	global_load_dwordx4 v[104:107], v216, s[42:43] offset:32
	global_load_dwordx4 v[108:111], v216, s[42:43] offset:48
	s_mov_b64 exec, -1
	v_add_u32_e32 v212, 128, v217
	v_max_i32_e32 v212, 0, v212
	v_min_u32_e32 v212, 0x1fff, v212
	v_mul_lo_u32 v172, v212, s60
	v_add_u32_e32 v172, v172, v4
	global_load_dwordx4 v[32:35], v172, s[38:39] offset:2048
	global_load_dwordx4 v[36:39], v172, s[38:39] offset:2560
	v_lshlrev_b32_e32 v216, 6, v212
	s_mov_b64 exec, s[62:63]
	global_load_dwordx4 v[116:119], v216, s[42:43] offset:0
	global_load_dwordx4 v[120:123], v216, s[42:43] offset:16
	global_load_dwordx4 v[124:127], v216, s[42:43] offset:32
	global_load_dwordx4 v[128:131], v216, s[42:43] offset:48
	s_mov_b64 exec, -1
	v_add_u32_e32 v212, 192, v217
	v_max_i32_e32 v212, 0, v212
	v_min_u32_e32 v212, 0x1fff, v212
	v_mul_lo_u32 v172, v212, s60
	v_add_u32_e32 v172, v172, v4
	global_load_dwordx4 v[40:43], v172, s[38:39] offset:2048
	global_load_dwordx4 v[44:47], v172, s[38:39] offset:2560
	v_lshlrev_b32_e32 v216, 6, v212
	s_mov_b64 exec, s[62:63]
	global_load_dwordx4 v[132:135], v216, s[42:43] offset:0
	global_load_dwordx4 v[136:139], v216, s[42:43] offset:16
	global_load_dwordx4 v[140:143], v216, s[42:43] offset:32
	global_load_dwordx4 v[144:147], v216, s[42:43] offset:48
	s_mov_b64 exec, -1
	v_add_u32_e32 v212, 256, v217
	v_max_i32_e32 v212, 0, v212
	v_min_u32_e32 v212, 0x1fff, v212
	v_mul_lo_u32 v172, v212, s60
	v_add_u32_e32 v172, v172, v4
	global_load_dwordx4 v[164:167], v172, s[38:39] offset:2048
	global_load_dwordx4 v[168:171], v172, s[38:39] offset:2560
	v_lshlrev_b32_e32 v216, 6, v212
	s_mov_b64 exec, s[62:63]
	global_load_dwordx4 v[148:151], v216, s[42:43] offset:0
	global_load_dwordx4 v[152:155], v216, s[42:43] offset:16
	global_load_dwordx4 v[156:159], v216, s[42:43] offset:32
	global_load_dwordx4 v[160:163], v216, s[42:43] offset:48
	s_mov_b64 exec, -1
	v_add_u32_e32 v212, 320, v217
	v_max_i32_e32 v212, 0, v212
	v_min_u32_e32 v212, 0x1fff, v212
	v_mul_lo_u32 v172, v212, s60
	v_add_u32_e32 v172, v172, v4
	global_load_dwordx4 v[208:211], v172, s[38:39] offset:2048
	global_load_dwordx4 v[222:225], v172, s[38:39] offset:2560
	v_lshlrev_b32_e32 v216, 6, v212
	s_mov_b64 exec, s[62:63]
	global_load_dwordx4 v[176:179], v216, s[42:43] offset:0
	global_load_dwordx4 v[180:183], v216, s[42:43] offset:16
	global_load_dwordx4 v[184:187], v216, s[42:43] offset:32
	global_load_dwordx4 v[188:191], v216, s[42:43] offset:48
	s_mov_b64 exec, -1
	s_cmp_eq_u32 s53, 0
	s_cbranch_scc1 .Lat_skip0_3
	s_waitcnt vmcnt(30)
	v_lshlrev_b32_e32 v56, 16, v16
	v_and_b32_e32 v57, 0xffff0000, v16
	v_lshlrev_b32_e32 v58, 16, v17
	v_and_b32_e32 v59, 0xffff0000, v17
	v_lshlrev_b32_e32 v60, 16, v18
	v_and_b32_e32 v61, 0xffff0000, v18
	v_lshlrev_b32_e32 v62, 16, v19
	v_and_b32_e32 v63, 0xffff0000, v19
	v_mul_f32_e32 v72, v56, v56
	v_fmac_f32_e32 v72, v57, v57
	v_fmac_f32_e32 v72, v58, v58
	v_fmac_f32_e32 v72, v59, v59
	v_fmac_f32_e32 v72, v60, v60
	v_fmac_f32_e32 v72, v61, v61
	v_fmac_f32_e32 v72, v62, v62
	v_fmac_f32_e32 v72, v63, v63
	s_add_u32 s4, s83, 0
	s_and_b32 s4, s4, 0x1ff
	s_mul_i32 s4, s4, 0x90
	v_add_f32_dpp v72, v72, v72 quad_perm:[1,0,3,2] row_mask:0xf bank_mask:0xf
	s_nop 1
	v_add_f32_dpp v72, v72, v72 quad_perm:[2,3,0,1] row_mask:0xf bank_mask:0xf
	s_nop 1
	v_add_f32_dpp v72, v72, v72 row_half_mirror row_mask:0xf bank_mask:0xf
	s_nop 1
	v_fmamk_f32 v72, v72, 0x3c800000, v174
	v_rsq_f32_e32 v73, v72
	v_add_u32_e32 v212, s4, v5
	v_add_u32_e32 v216, 0x12000, v212
	v_mul_f32_e32 v56, v56, v73
	v_mul_f32_e32 v57, v57, v73
	v_mul_f32_e32 v58, v58, v73
	v_mul_f32_e32 v59, v59, v73
	v_mul_f32_e32 v60, v60, v73
	v_mul_f32_e32 v61, v61, v73
	v_mul_f32_e32 v62, v62, v73
	v_mul_f32_e32 v63, v63, v73
	v_mul_f32_e32 v56, v56, v48
	v_mul_f32_e32 v57, v57, v49
	v_mul_f32_e32 v58, v58, v50
	v_mul_f32_e32 v59, v59, v51
	v_mul_f32_e32 v60, v60, v52
	v_mul_f32_e32 v61, v61, v53
	v_mul_f32_e32 v62, v62, v54
	v_mul_f32_e32 v63, v63, v55
	s_mov_b64 exec, s[62:63]
	s_nop 4
	v_mov_b32_dpp v64, v56 quad_perm:[1,0,3,2] row_mask:0xf bank_mask:0xf
	v_mov_b32_dpp v65, v57 quad_perm:[1,0,3,2] row_mask:0xf bank_mask:0xf
	v_mov_b32_dpp v66, v58 quad_perm:[1,0,3,2] row_mask:0xf bank_mask:0xf
	v_mov_b32_dpp v67, v59 quad_perm:[1,0,3,2] row_mask:0xf bank_mask:0xf
	v_mov_b32_dpp v68, v60 quad_perm:[1,0,3,2] row_mask:0xf bank_mask:0xf
	v_mov_b32_dpp v69, v61 quad_perm:[1,0,3,2] row_mask:0xf bank_mask:0xf
	v_mov_b32_dpp v70, v62 quad_perm:[1,0,3,2] row_mask:0xf bank_mask:0xf
	v_mov_b32_dpp v71, v63 quad_perm:[1,0,3,2] row_mask:0xf bank_mask:0xf
	s_nop 0
	v_mul_f32_e32 v64, v64, v81
	v_mul_f32_e32 v65, v65, v83
	v_mul_f32_e32 v66, v66, v85
	v_mul_f32_e32 v67, v67, v87
	v_mul_f32_e32 v68, v68, v89
	v_mul_f32_e32 v69, v69, v91
	v_mul_f32_e32 v70, v70, v93
	v_mul_f32_e32 v71, v71, v95
	v_cndmask_b32_e64 v64, v64, -v64, s[64:65]
	v_cndmask_b32_e64 v65, v65, -v65, s[64:65]
	v_cndmask_b32_e64 v66, v66, -v66, s[64:65]
	v_cndmask_b32_e64 v67, v67, -v67, s[64:65]
	v_cndmask_b32_e64 v68, v68, -v68, s[64:65]
	v_cndmask_b32_e64 v69, v69, -v69, s[64:65]
	v_cndmask_b32_e64 v70, v70, -v70, s[64:65]
	v_cndmask_b32_e64 v71, v71, -v71, s[64:65]
	v_fma_f32 v56, v56, v80, v64
	v_fma_f32 v57, v57, v82, v65
	v_fma_f32 v58, v58, v84, v66
	v_fma_f32 v59, v59, v86, v67
	v_fma_f32 v60, v60, v88, v68
	v_fma_f32 v61, v61, v90, v69
	v_fma_f32 v62, v62, v92, v70
	v_fma_f32 v63, v63, v94, v71
	s_mov_b64 exec, -1
	v_cvt_pk_bf16_f32 v76, v56, v57
	v_cvt_pk_bf16_f32 v77, v58, v59
	v_cvt_pk_bf16_f32 v78, v60, v61
	v_cvt_pk_bf16_f32 v79, v62, v63
	ds_write_b128 v212, v[76:79]
	ds_write_b128 v216, v[20:23]
.Lat_skip0_3:
	s_cmp_eq_u32 s53, 0
	s_cbranch_scc1 .Lat_skip1_4
	s_waitcnt vmcnt(24)
	v_lshlrev_b32_e32 v56, 16, v24
	v_and_b32_e32 v57, 0xffff0000, v24
	v_lshlrev_b32_e32 v58, 16, v25
	v_and_b32_e32 v59, 0xffff0000, v25
	v_lshlrev_b32_e32 v60, 16, v26
	v_and_b32_e32 v61, 0xffff0000, v26
	v_lshlrev_b32_e32 v62, 16, v27
	v_and_b32_e32 v63, 0xffff0000, v27
	v_mul_f32_e32 v72, v56, v56
	v_fmac_f32_e32 v72, v57, v57
	v_fmac_f32_e32 v72, v58, v58
	v_fmac_f32_e32 v72, v59, v59
	v_fmac_f32_e32 v72, v60, v60
	v_fmac_f32_e32 v72, v61, v61
	v_fmac_f32_e32 v72, v62, v62
	v_fmac_f32_e32 v72, v63, v63
	s_add_u32 s4, s83, 64
	s_and_b32 s4, s4, 0x1ff
	s_mul_i32 s4, s4, 0x90
	v_add_f32_dpp v72, v72, v72 quad_perm:[1,0,3,2] row_mask:0xf bank_mask:0xf
	s_nop 1
	v_add_f32_dpp v72, v72, v72 quad_perm:[2,3,0,1] row_mask:0xf bank_mask:0xf
	s_nop 1
	v_add_f32_dpp v72, v72, v72 row_half_mirror row_mask:0xf bank_mask:0xf
	s_nop 1
	v_fmamk_f32 v72, v72, 0x3c800000, v174
	v_rsq_f32_e32 v73, v72
	v_add_u32_e32 v212, s4, v5
	v_add_u32_e32 v216, 0x12000, v212
	v_mul_f32_e32 v56, v56, v73
	v_mul_f32_e32 v57, v57, v73
	v_mul_f32_e32 v58, v58, v73
	v_mul_f32_e32 v59, v59, v73
	v_mul_f32_e32 v60, v60, v73
	v_mul_f32_e32 v61, v61, v73
	v_mul_f32_e32 v62, v62, v73
	v_mul_f32_e32 v63, v63, v73
	v_mul_f32_e32 v56, v56, v48
	v_mul_f32_e32 v57, v57, v49
	v_mul_f32_e32 v58, v58, v50
	v_mul_f32_e32 v59, v59, v51
	v_mul_f32_e32 v60, v60, v52
	v_mul_f32_e32 v61, v61, v53
	v_mul_f32_e32 v62, v62, v54
	v_mul_f32_e32 v63, v63, v55
	s_mov_b64 exec, s[62:63]
	s_nop 4
	v_mov_b32_dpp v64, v56 quad_perm:[1,0,3,2] row_mask:0xf bank_mask:0xf
	v_mov_b32_dpp v65, v57 quad_perm:[1,0,3,2] row_mask:0xf bank_mask:0xf
	v_mov_b32_dpp v66, v58 quad_perm:[1,0,3,2] row_mask:0xf bank_mask:0xf
	v_mov_b32_dpp v67, v59 quad_perm:[1,0,3,2] row_mask:0xf bank_mask:0xf
	v_mov_b32_dpp v68, v60 quad_perm:[1,0,3,2] row_mask:0xf bank_mask:0xf
	v_mov_b32_dpp v69, v61 quad_perm:[1,0,3,2] row_mask:0xf bank_mask:0xf
	v_mov_b32_dpp v70, v62 quad_perm:[1,0,3,2] row_mask:0xf bank_mask:0xf
	v_mov_b32_dpp v71, v63 quad_perm:[1,0,3,2] row_mask:0xf bank_mask:0xf
	s_nop 0
	v_mul_f32_e32 v64, v64, v97
	v_mul_f32_e32 v65, v65, v99
	v_mul_f32_e32 v66, v66, v101
	v_mul_f32_e32 v67, v67, v103
	v_mul_f32_e32 v68, v68, v105
	v_mul_f32_e32 v69, v69, v107
	v_mul_f32_e32 v70, v70, v109
	v_mul_f32_e32 v71, v71, v111
	v_cndmask_b32_e64 v64, v64, -v64, s[64:65]
	v_cndmask_b32_e64 v65, v65, -v65, s[64:65]
	v_cndmask_b32_e64 v66, v66, -v66, s[64:65]
	v_cndmask_b32_e64 v67, v67, -v67, s[64:65]
	v_cndmask_b32_e64 v68, v68, -v68, s[64:65]
	v_cndmask_b32_e64 v69, v69, -v69, s[64:65]
	v_cndmask_b32_e64 v70, v70, -v70, s[64:65]
	v_cndmask_b32_e64 v71, v71, -v71, s[64:65]
	v_fma_f32 v56, v56, v96, v64
	v_fma_f32 v57, v57, v98, v65
	v_fma_f32 v58, v58, v100, v66
	v_fma_f32 v59, v59, v102, v67
	v_fma_f32 v60, v60, v104, v68
	v_fma_f32 v61, v61, v106, v69
	v_fma_f32 v62, v62, v108, v70
	v_fma_f32 v63, v63, v110, v71
	s_mov_b64 exec, -1
	v_cvt_pk_bf16_f32 v76, v56, v57
	v_cvt_pk_bf16_f32 v77, v58, v59
	v_cvt_pk_bf16_f32 v78, v60, v61
	v_cvt_pk_bf16_f32 v79, v62, v63
	ds_write_b128 v212, v[76:79]
	ds_write_b128 v216, v[28:31]
.Lat_skip1_4:
	global_load_dwordx4 v[80:83], v12, s[72:73] offset:0
	global_load_dwordx4 v[84:87], v12, s[72:73] offset:16
	global_load_dwordx4 v[88:91], v12, s[72:73] offset:32
	global_load_dwordx4 v[92:95], v12, s[72:73] offset:48
	global_load_dwordx4 v[96:99], v12, s[72:73] offset:2048
	global_load_dwordx4 v[100:103], v12, s[72:73] offset:2064
	global_load_dwordx4 v[104:107], v12, s[72:73] offset:2080
	global_load_dwordx4 v[108:111], v12, s[72:73] offset:2096
	s_waitcnt vmcnt(26)
	v_lshlrev_b32_e32 v56, 16, v32
	v_and_b32_e32 v57, 0xffff0000, v32
	v_lshlrev_b32_e32 v58, 16, v33
	v_and_b32_e32 v59, 0xffff0000, v33
	v_lshlrev_b32_e32 v60, 16, v34
	v_and_b32_e32 v61, 0xffff0000, v34
	v_lshlrev_b32_e32 v62, 16, v35
	v_and_b32_e32 v63, 0xffff0000, v35
	v_mul_f32_e32 v72, v56, v56
	v_fmac_f32_e32 v72, v57, v57
	v_fmac_f32_e32 v72, v58, v58
	v_fmac_f32_e32 v72, v59, v59
	v_fmac_f32_e32 v72, v60, v60
	v_fmac_f32_e32 v72, v61, v61
	v_fmac_f32_e32 v72, v62, v62
	v_fmac_f32_e32 v72, v63, v63
	s_add_u32 s4, s83, 128
	s_and_b32 s4, s4, 0x1ff
	s_mul_i32 s4, s4, 0x90
	v_add_f32_dpp v72, v72, v72 quad_perm:[1,0,3,2] row_mask:0xf bank_mask:0xf
	s_nop 1
	v_add_f32_dpp v72, v72, v72 quad_perm:[2,3,0,1] row_mask:0xf bank_mask:0xf
	s_nop 1
	v_add_f32_dpp v72, v72, v72 row_half_mirror row_mask:0xf bank_mask:0xf
	s_nop 1
	v_fmamk_f32 v72, v72, 0x3c800000, v174
	v_rsq_f32_e32 v73, v72
	v_add_u32_e32 v212, s4, v5
	v_add_u32_e32 v216, 0x12000, v212
	v_mul_f32_e32 v56, v56, v73
	v_mul_f32_e32 v57, v57, v73
	v_mul_f32_e32 v58, v58, v73
	v_mul_f32_e32 v59, v59, v73
	v_mul_f32_e32 v60, v60, v73
	v_mul_f32_e32 v61, v61, v73
	v_mul_f32_e32 v62, v62, v73
	v_mul_f32_e32 v63, v63, v73
	v_mul_f32_e32 v56, v56, v48
	v_mul_f32_e32 v57, v57, v49
	v_mul_f32_e32 v58, v58, v50
	v_mul_f32_e32 v59, v59, v51
	v_mul_f32_e32 v60, v60, v52
	v_mul_f32_e32 v61, v61, v53
	v_mul_f32_e32 v62, v62, v54
	v_mul_f32_e32 v63, v63, v55
	s_mov_b64 exec, s[62:63]
	s_nop 4
	v_mov_b32_dpp v64, v56 quad_perm:[1,0,3,2] row_mask:0xf bank_mask:0xf
	v_mov_b32_dpp v65, v57 quad_perm:[1,0,3,2] row_mask:0xf bank_mask:0xf
	v_mov_b32_dpp v66, v58 quad_perm:[1,0,3,2] row_mask:0xf bank_mask:0xf
	v_mov_b32_dpp v67, v59 quad_perm:[1,0,3,2] row_mask:0xf bank_mask:0xf
	v_mov_b32_dpp v68, v60 quad_perm:[1,0,3,2] row_mask:0xf bank_mask:0xf
	v_mov_b32_dpp v69, v61 quad_perm:[1,0,3,2] row_mask:0xf bank_mask:0xf
	v_mov_b32_dpp v70, v62 quad_perm:[1,0,3,2] row_mask:0xf bank_mask:0xf
	v_mov_b32_dpp v71, v63 quad_perm:[1,0,3,2] row_mask:0xf bank_mask:0xf
	s_nop 0
	v_mul_f32_e32 v64, v64, v117
	v_mul_f32_e32 v65, v65, v119
	v_mul_f32_e32 v66, v66, v121
	v_mul_f32_e32 v67, v67, v123
	v_mul_f32_e32 v68, v68, v125
	v_mul_f32_e32 v69, v69, v127
	v_mul_f32_e32 v70, v70, v129
	v_mul_f32_e32 v71, v71, v131
	v_cndmask_b32_e64 v64, v64, -v64, s[64:65]
	v_cndmask_b32_e64 v65, v65, -v65, s[64:65]
	v_cndmask_b32_e64 v66, v66, -v66, s[64:65]
	v_cndmask_b32_e64 v67, v67, -v67, s[64:65]
	v_cndmask_b32_e64 v68, v68, -v68, s[64:65]
	v_cndmask_b32_e64 v69, v69, -v69, s[64:65]
	v_cndmask_b32_e64 v70, v70, -v70, s[64:65]
	v_cndmask_b32_e64 v71, v71, -v71, s[64:65]
	v_fma_f32 v56, v56, v116, v64
	v_fma_f32 v57, v57, v118, v65
	v_fma_f32 v58, v58, v120, v66
	v_fma_f32 v59, v59, v122, v67
	v_fma_f32 v60, v60, v124, v68
	v_fma_f32 v61, v61, v126, v69
	v_fma_f32 v62, v62, v128, v70
	v_fma_f32 v63, v63, v130, v71
	s_mov_b64 exec, -1
	v_cvt_pk_bf16_f32 v76, v56, v57
	v_cvt_pk_bf16_f32 v77, v58, v59
	v_cvt_pk_bf16_f32 v78, v60, v61
	v_cvt_pk_bf16_f32 v79, v62, v63
	ds_write_b128 v212, v[76:79]
	ds_write_b128 v216, v[36:39]
.Lat_skip2_5:
	s_waitcnt vmcnt(20)
	v_lshlrev_b32_e32 v56, 16, v40
	v_and_b32_e32 v57, 0xffff0000, v40
	v_lshlrev_b32_e32 v58, 16, v41
	v_and_b32_e32 v59, 0xffff0000, v41
	v_lshlrev_b32_e32 v60, 16, v42
	v_and_b32_e32 v61, 0xffff0000, v42
	v_lshlrev_b32_e32 v62, 16, v43
	v_and_b32_e32 v63, 0xffff0000, v43
	v_mul_f32_e32 v72, v56, v56
	v_fmac_f32_e32 v72, v57, v57
	v_fmac_f32_e32 v72, v58, v58
	v_fmac_f32_e32 v72, v59, v59
	v_fmac_f32_e32 v72, v60, v60
	v_fmac_f32_e32 v72, v61, v61
	v_fmac_f32_e32 v72, v62, v62
	v_fmac_f32_e32 v72, v63, v63
	s_add_u32 s4, s83, 192
	s_and_b32 s4, s4, 0x1ff
	s_mul_i32 s4, s4, 0x90
	v_add_f32_dpp v72, v72, v72 quad_perm:[1,0,3,2] row_mask:0xf bank_mask:0xf
	s_nop 1
	v_add_f32_dpp v72, v72, v72 quad_perm:[2,3,0,1] row_mask:0xf bank_mask:0xf
	s_nop 1
	v_add_f32_dpp v72, v72, v72 row_half_mirror row_mask:0xf bank_mask:0xf
	s_nop 1
	v_fmamk_f32 v72, v72, 0x3c800000, v174
	v_rsq_f32_e32 v73, v72
	v_add_u32_e32 v212, s4, v5
	v_add_u32_e32 v216, 0x12000, v212
	v_mul_f32_e32 v56, v56, v73
	v_mul_f32_e32 v57, v57, v73
	v_mul_f32_e32 v58, v58, v73
	v_mul_f32_e32 v59, v59, v73
	v_mul_f32_e32 v60, v60, v73
	v_mul_f32_e32 v61, v61, v73
	v_mul_f32_e32 v62, v62, v73
	v_mul_f32_e32 v63, v63, v73
	v_mul_f32_e32 v56, v56, v48
	v_mul_f32_e32 v57, v57, v49
	v_mul_f32_e32 v58, v58, v50
	v_mul_f32_e32 v59, v59, v51
	v_mul_f32_e32 v60, v60, v52
	v_mul_f32_e32 v61, v61, v53
	v_mul_f32_e32 v62, v62, v54
	v_mul_f32_e32 v63, v63, v55
	s_mov_b64 exec, s[62:63]
	s_nop 4
	v_mov_b32_dpp v64, v56 quad_perm:[1,0,3,2] row_mask:0xf bank_mask:0xf
	v_mov_b32_dpp v65, v57 quad_perm:[1,0,3,2] row_mask:0xf bank_mask:0xf
	v_mov_b32_dpp v66, v58 quad_perm:[1,0,3,2] row_mask:0xf bank_mask:0xf
	v_mov_b32_dpp v67, v59 quad_perm:[1,0,3,2] row_mask:0xf bank_mask:0xf
	v_mov_b32_dpp v68, v60 quad_perm:[1,0,3,2] row_mask:0xf bank_mask:0xf
	v_mov_b32_dpp v69, v61 quad_perm:[1,0,3,2] row_mask:0xf bank_mask:0xf
	v_mov_b32_dpp v70, v62 quad_perm:[1,0,3,2] row_mask:0xf bank_mask:0xf
	v_mov_b32_dpp v71, v63 quad_perm:[1,0,3,2] row_mask:0xf bank_mask:0xf
	s_nop 0
	v_mul_f32_e32 v64, v64, v133
	v_mul_f32_e32 v65, v65, v135
	v_mul_f32_e32 v66, v66, v137
	v_mul_f32_e32 v67, v67, v139
	v_mul_f32_e32 v68, v68, v141
	v_mul_f32_e32 v69, v69, v143
	v_mul_f32_e32 v70, v70, v145
	v_mul_f32_e32 v71, v71, v147
	v_cndmask_b32_e64 v64, v64, -v64, s[64:65]
	v_cndmask_b32_e64 v65, v65, -v65, s[64:65]
	v_cndmask_b32_e64 v66, v66, -v66, s[64:65]
	v_cndmask_b32_e64 v67, v67, -v67, s[64:65]
	v_cndmask_b32_e64 v68, v68, -v68, s[64:65]
	v_cndmask_b32_e64 v69, v69, -v69, s[64:65]
	v_cndmask_b32_e64 v70, v70, -v70, s[64:65]
	v_cndmask_b32_e64 v71, v71, -v71, s[64:65]
	v_fma_f32 v56, v56, v132, v64
	v_fma_f32 v57, v57, v134, v65
	v_fma_f32 v58, v58, v136, v66
	v_fma_f32 v59, v59, v138, v67
	v_fma_f32 v60, v60, v140, v68
	v_fma_f32 v61, v61, v142, v69
	v_fma_f32 v62, v62, v144, v70
	v_fma_f32 v63, v63, v146, v71
	s_mov_b64 exec, -1
	v_cvt_pk_bf16_f32 v76, v56, v57
	v_cvt_pk_bf16_f32 v77, v58, v59
	v_cvt_pk_bf16_f32 v78, v60, v61
	v_cvt_pk_bf16_f32 v79, v62, v63
	ds_write_b128 v212, v[76:79]
	ds_write_b128 v216, v[44:47]
.Lat_skip3_6:
	v_lshlrev_b32_e32 v212, 5, v2
	global_load_dwordx4 v[16:19], v212, s[48:49] offset:0
	global_load_dwordx4 v[20:23], v212, s[48:49] offset:16
	global_load_dwordx4 v[24:27], v212, s[48:49] offset:64
	global_load_dwordx4 v[28:31], v212, s[48:49] offset:80
	global_load_dwordx4 v[32:35], v212, s[48:49] offset:128
	global_load_dwordx4 v[36:39], v212, s[48:49] offset:144
	global_load_dwordx4 v[40:43], v212, s[48:49] offset:192
	global_load_dwordx4 v[44:47], v212, s[48:49] offset:208
	s_cmp_eq_u32 s53, 63
	s_cbranch_scc1 .Lat_skip4_7
	s_waitcnt vmcnt(22)
	v_lshlrev_b32_e32 v56, 16, v164
	v_and_b32_e32 v57, 0xffff0000, v164
	v_lshlrev_b32_e32 v58, 16, v165
	v_and_b32_e32 v59, 0xffff0000, v165
	v_lshlrev_b32_e32 v60, 16, v166
	v_and_b32_e32 v61, 0xffff0000, v166
	v_lshlrev_b32_e32 v62, 16, v167
	v_and_b32_e32 v63, 0xffff0000, v167
	v_mul_f32_e32 v72, v56, v56
	v_fmac_f32_e32 v72, v57, v57
	v_fmac_f32_e32 v72, v58, v58
	v_fmac_f32_e32 v72, v59, v59
	v_fmac_f32_e32 v72, v60, v60
	v_fmac_f32_e32 v72, v61, v61
	v_fmac_f32_e32 v72, v62, v62
	v_fmac_f32_e32 v72, v63, v63
	s_add_u32 s4, s83, 256
	s_and_b32 s4, s4, 0x1ff
	s_mul_i32 s4, s4, 0x90
	v_add_f32_dpp v72, v72, v72 quad_perm:[1,0,3,2] row_mask:0xf bank_mask:0xf
	s_nop 1
	v_add_f32_dpp v72, v72, v72 quad_perm:[2,3,0,1] row_mask:0xf bank_mask:0xf
	s_nop 1
	v_add_f32_dpp v72, v72, v72 row_half_mirror row_mask:0xf bank_mask:0xf
	s_nop 1
	v_fmamk_f32 v72, v72, 0x3c800000, v174
	v_rsq_f32_e32 v73, v72
	v_add_u32_e32 v212, s4, v5
	v_add_u32_e32 v216, 0x12000, v212
	v_mul_f32_e32 v56, v56, v73
	v_mul_f32_e32 v57, v57, v73
	v_mul_f32_e32 v58, v58, v73
	v_mul_f32_e32 v59, v59, v73
	v_mul_f32_e32 v60, v60, v73
	v_mul_f32_e32 v61, v61, v73
	v_mul_f32_e32 v62, v62, v73
	v_mul_f32_e32 v63, v63, v73
	v_mul_f32_e32 v56, v56, v48
	v_mul_f32_e32 v57, v57, v49
	v_mul_f32_e32 v58, v58, v50
	v_mul_f32_e32 v59, v59, v51
	v_mul_f32_e32 v60, v60, v52
	v_mul_f32_e32 v61, v61, v53
	v_mul_f32_e32 v62, v62, v54
	v_mul_f32_e32 v63, v63, v55
	s_mov_b64 exec, s[62:63]
	s_nop 4
	v_mov_b32_dpp v64, v56 quad_perm:[1,0,3,2] row_mask:0xf bank_mask:0xf
	v_mov_b32_dpp v65, v57 quad_perm:[1,0,3,2] row_mask:0xf bank_mask:0xf
	v_mov_b32_dpp v66, v58 quad_perm:[1,0,3,2] row_mask:0xf bank_mask:0xf
	v_mov_b32_dpp v67, v59 quad_perm:[1,0,3,2] row_mask:0xf bank_mask:0xf
	v_mov_b32_dpp v68, v60 quad_perm:[1,0,3,2] row_mask:0xf bank_mask:0xf
	v_mov_b32_dpp v69, v61 quad_perm:[1,0,3,2] row_mask:0xf bank_mask:0xf
	v_mov_b32_dpp v70, v62 quad_perm:[1,0,3,2] row_mask:0xf bank_mask:0xf
	v_mov_b32_dpp v71, v63 quad_perm:[1,0,3,2] row_mask:0xf bank_mask:0xf
	s_nop 0
	v_mul_f32_e32 v64, v64, v149
	v_mul_f32_e32 v65, v65, v151
	v_mul_f32_e32 v66, v66, v153
	v_mul_f32_e32 v67, v67, v155
	v_mul_f32_e32 v68, v68, v157
	v_mul_f32_e32 v69, v69, v159
	v_mul_f32_e32 v70, v70, v161
	v_mul_f32_e32 v71, v71, v163
	v_cndmask_b32_e64 v64, v64, -v64, s[64:65]
	v_cndmask_b32_e64 v65, v65, -v65, s[64:65]
	v_cndmask_b32_e64 v66, v66, -v66, s[64:65]
	v_cndmask_b32_e64 v67, v67, -v67, s[64:65]
	v_cndmask_b32_e64 v68, v68, -v68, s[64:65]
	v_cndmask_b32_e64 v69, v69, -v69, s[64:65]
	v_cndmask_b32_e64 v70, v70, -v70, s[64:65]
	v_cndmask_b32_e64 v71, v71, -v71, s[64:65]
	v_fma_f32 v56, v56, v148, v64
	v_fma_f32 v57, v57, v150, v65
	v_fma_f32 v58, v58, v152, v66
	v_fma_f32 v59, v59, v154, v67
	v_fma_f32 v60, v60, v156, v68
	v_fma_f32 v61, v61, v158, v69
	v_fma_f32 v62, v62, v160, v70
	v_fma_f32 v63, v63, v162, v71
	s_mov_b64 exec, -1
	v_cvt_pk_bf16_f32 v76, v56, v57
	v_cvt_pk_bf16_f32 v77, v58, v59
	v_cvt_pk_bf16_f32 v78, v60, v61
	v_cvt_pk_bf16_f32 v79, v62, v63
	ds_write_b128 v212, v[76:79]
	ds_write_b128 v216, v[168:171]
.Lat_skip4_7:
	s_cmp_eq_u32 s53, 63
	s_cbranch_scc1 .Lat_skip5_8
	s_waitcnt vmcnt(16)
	v_lshlrev_b32_e32 v56, 16, v208
	v_and_b32_e32 v57, 0xffff0000, v208
	v_lshlrev_b32_e32 v58, 16, v209
	v_and_b32_e32 v59, 0xffff0000, v209
	v_lshlrev_b32_e32 v60, 16, v210
	v_and_b32_e32 v61, 0xffff0000, v210
	v_lshlrev_b32_e32 v62, 16, v211
	v_and_b32_e32 v63, 0xffff0000, v211
	v_mul_f32_e32 v72, v56, v56
	v_fmac_f32_e32 v72, v57, v57
	v_fmac_f32_e32 v72, v58, v58
	v_fmac_f32_e32 v72, v59, v59
	v_fmac_f32_e32 v72, v60, v60
	v_fmac_f32_e32 v72, v61, v61
	v_fmac_f32_e32 v72, v62, v62
	v_fmac_f32_e32 v72, v63, v63
	s_add_u32 s4, s83, 320
	s_and_b32 s4, s4, 0x1ff
	s_mul_i32 s4, s4, 0x90
	v_add_f32_dpp v72, v72, v72 quad_perm:[1,0,3,2] row_mask:0xf bank_mask:0xf
	s_nop 1
	v_add_f32_dpp v72, v72, v72 quad_perm:[2,3,0,1] row_mask:0xf bank_mask:0xf
	s_nop 1
	v_add_f32_dpp v72, v72, v72 row_half_mirror row_mask:0xf bank_mask:0xf
	s_nop 1
	v_fmamk_f32 v72, v72, 0x3c800000, v174
	v_rsq_f32_e32 v73, v72
	v_add_u32_e32 v212, s4, v5
	v_add_u32_e32 v216, 0x12000, v212
	v_mul_f32_e32 v56, v56, v73
	v_mul_f32_e32 v57, v57, v73
	v_mul_f32_e32 v58, v58, v73
	v_mul_f32_e32 v59, v59, v73
	v_mul_f32_e32 v60, v60, v73
	v_mul_f32_e32 v61, v61, v73
	v_mul_f32_e32 v62, v62, v73
	v_mul_f32_e32 v63, v63, v73
	v_mul_f32_e32 v56, v56, v48
	v_mul_f32_e32 v57, v57, v49
	v_mul_f32_e32 v58, v58, v50
	v_mul_f32_e32 v59, v59, v51
	v_mul_f32_e32 v60, v60, v52
	v_mul_f32_e32 v61, v61, v53
	v_mul_f32_e32 v62, v62, v54
	v_mul_f32_e32 v63, v63, v55
	s_mov_b64 exec, s[62:63]
	s_nop 4
	v_mov_b32_dpp v64, v56 quad_perm:[1,0,3,2] row_mask:0xf bank_mask:0xf
	v_mov_b32_dpp v65, v57 quad_perm:[1,0,3,2] row_mask:0xf bank_mask:0xf
	v_mov_b32_dpp v66, v58 quad_perm:[1,0,3,2] row_mask:0xf bank_mask:0xf
	v_mov_b32_dpp v67, v59 quad_perm:[1,0,3,2] row_mask:0xf bank_mask:0xf
	v_mov_b32_dpp v68, v60 quad_perm:[1,0,3,2] row_mask:0xf bank_mask:0xf
	v_mov_b32_dpp v69, v61 quad_perm:[1,0,3,2] row_mask:0xf bank_mask:0xf
	v_mov_b32_dpp v70, v62 quad_perm:[1,0,3,2] row_mask:0xf bank_mask:0xf
	v_mov_b32_dpp v71, v63 quad_perm:[1,0,3,2] row_mask:0xf bank_mask:0xf
	s_nop 0
	v_mul_f32_e32 v64, v64, v177
	v_mul_f32_e32 v65, v65, v179
	v_mul_f32_e32 v66, v66, v181
	v_mul_f32_e32 v67, v67, v183
	v_mul_f32_e32 v68, v68, v185
	v_mul_f32_e32 v69, v69, v187
	v_mul_f32_e32 v70, v70, v189
	v_mul_f32_e32 v71, v71, v191
	v_cndmask_b32_e64 v64, v64, -v64, s[64:65]
	v_cndmask_b32_e64 v65, v65, -v65, s[64:65]
	v_cndmask_b32_e64 v66, v66, -v66, s[64:65]
	v_cndmask_b32_e64 v67, v67, -v67, s[64:65]
	v_cndmask_b32_e64 v68, v68, -v68, s[64:65]
	v_cndmask_b32_e64 v69, v69, -v69, s[64:65]
	v_cndmask_b32_e64 v70, v70, -v70, s[64:65]
	v_cndmask_b32_e64 v71, v71, -v71, s[64:65]
	v_fma_f32 v56, v56, v176, v64
	v_fma_f32 v57, v57, v178, v65
	v_fma_f32 v58, v58, v180, v66
	v_fma_f32 v59, v59, v182, v67
	v_fma_f32 v60, v60, v184, v68
	v_fma_f32 v61, v61, v186, v69
	v_fma_f32 v62, v62, v188, v70
	v_fma_f32 v63, v63, v190, v71
	s_mov_b64 exec, -1
	v_cvt_pk_bf16_f32 v76, v56, v57
	v_cvt_pk_bf16_f32 v77, v58, v59
	v_cvt_pk_bf16_f32 v78, v60, v61
	v_cvt_pk_bf16_f32 v79, v62, v63
	ds_write_b128 v212, v[76:79]
	ds_write_b128 v216, v[222:225]

.Lat_incr_1:
	v_lshlrev_b32_e32 v212, 1, v4
	global_load_dwordx4 v[48:51], v212, s[46:47]
	global_load_dwordx4 v[52:55], v212, s[46:47] offset:16
	v_add_u32_e32 v212, 256, v217
	v_max_i32_e32 v212, 0, v212
	v_min_u32_e32 v212, 0x1fff, v212
	v_lshlrev_b32_e32 v216, 6, v212
	s_mov_b64 exec, s[62:63]
	global_load_dwordx4 v[148:151], v216, s[42:43] offset:0
	global_load_dwordx4 v[152:155], v216, s[42:43] offset:16
	global_load_dwordx4 v[156:159], v216, s[42:43] offset:32
	global_load_dwordx4 v[160:163], v216, s[42:43] offset:48
	s_mov_b64 exec, -1
	v_add_u32_e32 v212, 320, v217
	v_max_i32_e32 v212, 0, v212
	v_min_u32_e32 v212, 0x1fff, v212
	v_lshlrev_b32_e32 v216, 6, v212
	s_mov_b64 exec, s[62:63]
	global_load_dwordx4 v[176:179], v216, s[42:43] offset:0
	global_load_dwordx4 v[180:183], v216, s[42:43] offset:16
	global_load_dwordx4 v[184:187], v216, s[42:43] offset:32
	global_load_dwordx4 v[188:191], v216, s[42:43] offset:48
	s_mov_b64 exec, -1
	global_load_dwordx4 v[80:83], v12, s[72:73] offset:0
	global_load_dwordx4 v[84:87], v12, s[72:73] offset:16
	global_load_dwordx4 v[88:91], v12, s[72:73] offset:32
	global_load_dwordx4 v[92:95], v12, s[72:73] offset:48
	global_load_dwordx4 v[96:99], v12, s[72:73] offset:2048
	global_load_dwordx4 v[100:103], v12, s[72:73] offset:2064
	global_load_dwordx4 v[104:107], v12, s[72:73] offset:2080
	global_load_dwordx4 v[108:111], v12, s[72:73] offset:2096
	v_lshlrev_b32_e32 v212, 5, v2
	global_load_dwordx4 v[16:19], v212, s[48:49] offset:0
	global_load_dwordx4 v[20:23], v212, s[48:49] offset:16
	global_load_dwordx4 v[24:27], v212, s[48:49] offset:64
	global_load_dwordx4 v[28:31], v212, s[48:49] offset:80
	global_load_dwordx4 v[32:35], v212, s[48:49] offset:128
	global_load_dwordx4 v[36:39], v212, s[48:49] offset:144
	global_load_dwordx4 v[40:43], v212, s[48:49] offset:192
	global_load_dwordx4 v[44:47], v212, s[48:49] offset:208
	s_cmp_eq_u32 s53, 63
	s_cbranch_scc1 .Lat_skip4_9
	s_waitcnt vmcnt(20)
	v_lshlrev_b32_e32 v56, 16, v164
	v_and_b32_e32 v57, 0xffff0000, v164
	v_lshlrev_b32_e32 v58, 16, v165
	v_and_b32_e32 v59, 0xffff0000, v165
	v_lshlrev_b32_e32 v60, 16, v166
	v_and_b32_e32 v61, 0xffff0000, v166
	v_lshlrev_b32_e32 v62, 16, v167
	v_and_b32_e32 v63, 0xffff0000, v167
	v_mul_f32_e32 v72, v56, v56
	v_fmac_f32_e32 v72, v57, v57
	v_fmac_f32_e32 v72, v58, v58
	v_fmac_f32_e32 v72, v59, v59
	v_fmac_f32_e32 v72, v60, v60
	v_fmac_f32_e32 v72, v61, v61
	v_fmac_f32_e32 v72, v62, v62
	v_fmac_f32_e32 v72, v63, v63
	s_add_u32 s4, s83, 256
	s_and_b32 s4, s4, 0x1ff
	s_mul_i32 s4, s4, 0x90
	v_add_f32_dpp v72, v72, v72 quad_perm:[1,0,3,2] row_mask:0xf bank_mask:0xf
	s_nop 1
	v_add_f32_dpp v72, v72, v72 quad_perm:[2,3,0,1] row_mask:0xf bank_mask:0xf
	s_nop 1
	v_add_f32_dpp v72, v72, v72 row_half_mirror row_mask:0xf bank_mask:0xf
	s_nop 1
	v_fmamk_f32 v72, v72, 0x3c800000, v174
	v_rsq_f32_e32 v73, v72
	v_add_u32_e32 v212, s4, v5
	v_add_u32_e32 v216, 0x12000, v212
	v_mul_f32_e32 v56, v56, v73
	v_mul_f32_e32 v57, v57, v73
	v_mul_f32_e32 v58, v58, v73
	v_mul_f32_e32 v59, v59, v73
	v_mul_f32_e32 v60, v60, v73
	v_mul_f32_e32 v61, v61, v73
	v_mul_f32_e32 v62, v62, v73
	v_mul_f32_e32 v63, v63, v73
	v_mul_f32_e32 v56, v56, v48
	v_mul_f32_e32 v57, v57, v49
	v_mul_f32_e32 v58, v58, v50
	v_mul_f32_e32 v59, v59, v51
	v_mul_f32_e32 v60, v60, v52
	v_mul_f32_e32 v61, v61, v53
	v_mul_f32_e32 v62, v62, v54
	v_mul_f32_e32 v63, v63, v55
	s_mov_b64 exec, s[62:63]
	s_nop 4
	v_mov_b32_dpp v64, v56 quad_perm:[1,0,3,2] row_mask:0xf bank_mask:0xf
	v_mov_b32_dpp v65, v57 quad_perm:[1,0,3,2] row_mask:0xf bank_mask:0xf
	v_mov_b32_dpp v66, v58 quad_perm:[1,0,3,2] row_mask:0xf bank_mask:0xf
	v_mov_b32_dpp v67, v59 quad_perm:[1,0,3,2] row_mask:0xf bank_mask:0xf
	v_mov_b32_dpp v68, v60 quad_perm:[1,0,3,2] row_mask:0xf bank_mask:0xf
	v_mov_b32_dpp v69, v61 quad_perm:[1,0,3,2] row_mask:0xf bank_mask:0xf
	v_mov_b32_dpp v70, v62 quad_perm:[1,0,3,2] row_mask:0xf bank_mask:0xf
	v_mov_b32_dpp v71, v63 quad_perm:[1,0,3,2] row_mask:0xf bank_mask:0xf
	s_nop 0
	v_mul_f32_e32 v64, v64, v149
	v_mul_f32_e32 v65, v65, v151
	v_mul_f32_e32 v66, v66, v153
	v_mul_f32_e32 v67, v67, v155
	v_mul_f32_e32 v68, v68, v157
	v_mul_f32_e32 v69, v69, v159
	v_mul_f32_e32 v70, v70, v161
	v_mul_f32_e32 v71, v71, v163
	v_cndmask_b32_e64 v64, v64, -v64, s[64:65]
	v_cndmask_b32_e64 v65, v65, -v65, s[64:65]
	v_cndmask_b32_e64 v66, v66, -v66, s[64:65]
	v_cndmask_b32_e64 v67, v67, -v67, s[64:65]
	v_cndmask_b32_e64 v68, v68, -v68, s[64:65]
	v_cndmask_b32_e64 v69, v69, -v69, s[64:65]
	v_cndmask_b32_e64 v70, v70, -v70, s[64:65]
	v_cndmask_b32_e64 v71, v71, -v71, s[64:65]
	v_fma_f32 v56, v56, v148, v64
	v_fma_f32 v57, v57, v150, v65
	v_fma_f32 v58, v58, v152, v66
	v_fma_f32 v59, v59, v154, v67
	v_fma_f32 v60, v60, v156, v68
	v_fma_f32 v61, v61, v158, v69
	v_fma_f32 v62, v62, v160, v70
	v_fma_f32 v63, v63, v162, v71
	s_mov_b64 exec, -1
	v_cvt_pk_bf16_f32 v76, v56, v57
	v_cvt_pk_bf16_f32 v77, v58, v59
	v_cvt_pk_bf16_f32 v78, v60, v61
	v_cvt_pk_bf16_f32 v79, v62, v63
	ds_write_b128 v212, v[76:79]
	ds_write_b128 v216, v[168:171]

.Lat_skip5_10:
.Lat_staged_2:
	s_waitcnt vmcnt(0)
	s_waitcnt lgkmcnt(0)
	v_lshlrev_b32_e32 v116, 16, v192
	v_and_b32_e32 v117, 0xffff0000, v192
	v_lshlrev_b32_e32 v118, 16, v193
	v_and_b32_e32 v119, 0xffff0000, v193
	v_lshlrev_b32_e32 v120, 16, v194
	v_and_b32_e32 v121, 0xffff0000, v194
	v_lshlrev_b32_e32 v122, 16, v195
	v_and_b32_e32 v123, 0xffff0000, v195
	v_lshlrev_b32_e32 v124, 16, v196
	v_and_b32_e32 v125, 0xffff0000, v196
	v_lshlrev_b32_e32 v126, 16, v197
	v_and_b32_e32 v127, 0xffff0000, v197
	v_lshlrev_b32_e32 v128, 16, v198
	v_and_b32_e32 v129, 0xffff0000, v198
	v_lshlrev_b32_e32 v130, 16, v199
	v_and_b32_e32 v131, 0xffff0000, v199
	v_lshlrev_b32_e32 v132, 16, v200
	v_and_b32_e32 v133, 0xffff0000, v200
	v_lshlrev_b32_e32 v134, 16, v201
	v_and_b32_e32 v135, 0xffff0000, v201
	v_lshlrev_b32_e32 v136, 16, v202
	v_and_b32_e32 v137, 0xffff0000, v202
	v_lshlrev_b32_e32 v138, 16, v203
	v_and_b32_e32 v139, 0xffff0000, v203
	v_lshlrev_b32_e32 v140, 16, v204
	v_and_b32_e32 v141, 0xffff0000, v204
	v_lshlrev_b32_e32 v142, 16, v205
	v_and_b32_e32 v143, 0xffff0000, v205
	v_lshlrev_b32_e32 v144, 16, v206
	v_and_b32_e32 v145, 0xffff0000, v206
	v_lshlrev_b32_e32 v146, 16, v207
	v_and_b32_e32 v147, 0xffff0000, v207
	v_mul_f32_e32 v56, v116, v116
	v_fmac_f32_e32 v56, v117, v117
	v_fmac_f32_e32 v56, v118, v118
	v_fmac_f32_e32 v56, v119, v119
	v_fmac_f32_e32 v56, v120, v120
	v_fmac_f32_e32 v56, v121, v121
	v_fmac_f32_e32 v56, v122, v122
	v_fmac_f32_e32 v56, v123, v123
	v_fmac_f32_e32 v56, v124, v124
	v_fmac_f32_e32 v56, v125, v125
	v_fmac_f32_e32 v56, v126, v126
	v_fmac_f32_e32 v56, v127, v127
	v_fmac_f32_e32 v56, v128, v128
	v_fmac_f32_e32 v56, v129, v129
	v_fmac_f32_e32 v56, v130, v130
	v_fmac_f32_e32 v56, v131, v131
	v_fmac_f32_e32 v56, v132, v132
	v_fmac_f32_e32 v56, v133, v133
	v_fmac_f32_e32 v56, v134, v134
	v_fmac_f32_e32 v56, v135, v135
	v_fmac_f32_e32 v56, v136, v136
	v_fmac_f32_e32 v56, v137, v137
	v_fmac_f32_e32 v56, v138, v138
	v_fmac_f32_e32 v56, v139, v139
	v_fmac_f32_e32 v56, v140, v140
	v_fmac_f32_e32 v56, v141, v141
	v_fmac_f32_e32 v56, v142, v142
	v_fmac_f32_e32 v56, v143, v143
	v_fmac_f32_e32 v56, v144, v144
	v_fmac_f32_e32 v56, v145, v145
	v_fmac_f32_e32 v56, v146, v146
	v_fmac_f32_e32 v56, v147, v147
	v_mov_b32_e32 v57, v56
	s_nop 1
	v_permlane32_swap_b32_e32 v57, v56
	v_add_f32_e32 v56, v57, v56
	v_fmamk_f32 v56, v56, 0x3c800000, v174
	v_rsq_f32_e32 v56, v56
	v_mov_b32_e32 v58, 0x3e38aa3b
	v_pk_mul_f32 v[116:117], v[116:117], v[56:57] op_sel_hi:[1,0]
	v_pk_mul_f32 v[118:119], v[118:119], v[56:57] op_sel_hi:[1,0]
	v_pk_mul_f32 v[120:121], v[120:121], v[56:57] op_sel_hi:[1,0]
	v_pk_mul_f32 v[122:123], v[122:123], v[56:57] op_sel_hi:[1,0]
	v_pk_mul_f32 v[124:125], v[124:125], v[56:57] op_sel_hi:[1,0]
	v_pk_mul_f32 v[126:127], v[126:127], v[56:57] op_sel_hi:[1,0]
	v_pk_mul_f32 v[128:129], v[128:129], v[56:57] op_sel_hi:[1,0]
	v_pk_mul_f32 v[130:131], v[130:131], v[56:57] op_sel_hi:[1,0]
	v_pk_mul_f32 v[132:133], v[132:133], v[56:57] op_sel_hi:[1,0]
	v_pk_mul_f32 v[134:135], v[134:135], v[56:57] op_sel_hi:[1,0]
	v_pk_mul_f32 v[136:137], v[136:137], v[56:57] op_sel_hi:[1,0]
	v_pk_mul_f32 v[138:139], v[138:139], v[56:57] op_sel_hi:[1,0]
	v_pk_mul_f32 v[140:141], v[140:141], v[56:57] op_sel_hi:[1,0]
	v_pk_mul_f32 v[142:143], v[142:143], v[56:57] op_sel_hi:[1,0]
	v_pk_mul_f32 v[144:145], v[144:145], v[56:57] op_sel_hi:[1,0]
	v_pk_mul_f32 v[146:147], v[146:147], v[56:57] op_sel_hi:[1,0]
	v_pk_mul_f32 v[116:117], v[116:117], v[16:17]
	v_pk_mul_f32 v[118:119], v[118:119], v[18:19]
	v_pk_mul_f32 v[120:121], v[120:121], v[20:21]
	v_pk_mul_f32 v[122:123], v[122:123], v[22:23]
	v_pk_mul_f32 v[124:125], v[124:125], v[24:25]
	v_pk_mul_f32 v[126:127], v[126:127], v[26:27]
	v_pk_mul_f32 v[128:129], v[128:129], v[28:29]
	v_pk_mul_f32 v[130:131], v[130:131], v[30:31]
	v_pk_mul_f32 v[132:133], v[132:133], v[32:33]
	v_pk_mul_f32 v[134:135], v[134:135], v[34:35]
	v_pk_mul_f32 v[136:137], v[136:137], v[36:37]
	v_pk_mul_f32 v[138:139], v[138:139], v[38:39]
	v_pk_mul_f32 v[140:141], v[140:141], v[40:41]
	v_pk_mul_f32 v[142:143], v[142:143], v[42:43]
	v_pk_mul_f32 v[144:145], v[144:145], v[44:45]
	v_pk_mul_f32 v[146:147], v[146:147], v[46:47]
	v_mov_b32_e32 v68, v116
	v_mov_b32_e32 v69, v116
	s_nop 1
	v_permlane32_swap_b32_e32 v68, v69
	v_cndmask_b32_e64 v60, v69, v68, s[66:67]
	v_mov_b32_e32 v68, v117
	v_mov_b32_e32 v69, v117
	s_nop 1
	v_permlane32_swap_b32_e32 v68, v69
	v_cndmask_b32_e64 v61, v69, v68, s[66:67]
	v_mov_b32_e32 v68, v118
	v_mov_b32_e32 v69, v118
	s_nop 1
	v_permlane32_swap_b32_e32 v68, v69
	v_cndmask_b32_e64 v62, v69, v68, s[66:67]
	v_mov_b32_e32 v68, v119
	v_mov_b32_e32 v69, v119
	s_nop 1
	v_permlane32_swap_b32_e32 v68, v69
	v_cndmask_b32_e64 v63, v69, v68, s[66:67]
	v_mov_b32_e32 v68, v120
	v_mov_b32_e32 v69, v120
	s_nop 1
	v_permlane32_swap_b32_e32 v68, v69
	v_cndmask_b32_e64 v64, v69, v68, s[66:67]
	v_mov_b32_e32 v68, v121
	v_mov_b32_e32 v69, v121
	s_nop 1
	v_permlane32_swap_b32_e32 v68, v69
	v_cndmask_b32_e64 v65, v69, v68, s[66:67]
	v_mov_b32_e32 v68, v122
	v_mov_b32_e32 v69, v122
	s_nop 1
	v_permlane32_swap_b32_e32 v68, v69
	v_cndmask_b32_e64 v66, v69, v68, s[66:67]
	v_mov_b32_e32 v68, v123
	v_mov_b32_e32 v69, v123
	s_nop 1
	v_permlane32_swap_b32_e32 v68, v69
	v_cndmask_b32_e64 v67, v69, v68, s[66:67]
	v_mul_f32_e32 v60, v60, v81
	v_mul_f32_e32 v61, v61, v83
	v_mul_f32_e32 v62, v62, v85
	v_mul_f32_e32 v63, v63, v87
	v_mul_f32_e32 v64, v64, v89
	v_mul_f32_e32 v65, v65, v91
	v_mul_f32_e32 v66, v66, v93
	v_mul_f32_e32 v67, v67, v95
	v_cndmask_b32_e64 v60, -v60, v60, s[66:67]
	v_cndmask_b32_e64 v61, -v61, v61, s[66:67]
	v_cndmask_b32_e64 v62, -v62, v62, s[66:67]
	v_cndmask_b32_e64 v63, -v63, v63, s[66:67]
	v_cndmask_b32_e64 v64, -v64, v64, s[66:67]
	v_cndmask_b32_e64 v65, -v65, v65, s[66:67]
	v_cndmask_b32_e64 v66, -v66, v66, s[66:67]
	v_cndmask_b32_e64 v67, -v67, v67, s[66:67]
	v_fma_f32 v116, v116, v80, v60
	v_fma_f32 v117, v117, v82, v61
	v_fma_f32 v118, v118, v84, v62
	v_fma_f32 v119, v119, v86, v63
	v_fma_f32 v120, v120, v88, v64
	v_fma_f32 v121, v121, v90, v65
	v_fma_f32 v122, v122, v92, v66
	v_fma_f32 v123, v123, v94, v67
	v_pk_mul_f32 v[116:117], v[116:117], v[58:59] op_sel_hi:[1,0]
	v_pk_mul_f32 v[118:119], v[118:119], v[58:59] op_sel_hi:[1,0]
	v_pk_mul_f32 v[120:121], v[120:121], v[58:59] op_sel_hi:[1,0]
	v_pk_mul_f32 v[122:123], v[122:123], v[58:59] op_sel_hi:[1,0]
	v_pk_mul_f32 v[124:125], v[124:125], v[58:59] op_sel_hi:[1,0]
	v_pk_mul_f32 v[126:127], v[126:127], v[58:59] op_sel_hi:[1,0]
	v_pk_mul_f32 v[128:129], v[128:129], v[58:59] op_sel_hi:[1,0]
	v_pk_mul_f32 v[130:131], v[130:131], v[58:59] op_sel_hi:[1,0]
	v_pk_mul_f32 v[132:133], v[132:133], v[58:59] op_sel_hi:[1,0]
	v_pk_mul_f32 v[134:135], v[134:135], v[58:59] op_sel_hi:[1,0]
	v_pk_mul_f32 v[136:137], v[136:137], v[58:59] op_sel_hi:[1,0]
	v_pk_mul_f32 v[138:139], v[138:139], v[58:59] op_sel_hi:[1,0]
	v_pk_mul_f32 v[140:141], v[140:141], v[58:59] op_sel_hi:[1,0]
	v_pk_mul_f32 v[142:143], v[142:143], v[58:59] op_sel_hi:[1,0]
	v_pk_mul_f32 v[144:145], v[144:145], v[58:59] op_sel_hi:[1,0]
	v_pk_mul_f32 v[146:147], v[146:147], v[58:59] op_sel_hi:[1,0]
	v_cvt_pk_bf16_f32 v116, v116, v117
	v_cvt_pk_bf16_f32 v117, v118, v119
	v_cvt_pk_bf16_f32 v118, v120, v121
	v_cvt_pk_bf16_f32 v119, v122, v123
	v_cvt_pk_bf16_f32 v120, v124, v125
	v_cvt_pk_bf16_f32 v121, v126, v127
	v_cvt_pk_bf16_f32 v122, v128, v129
	v_cvt_pk_bf16_f32 v123, v130, v131
	v_cvt_pk_bf16_f32 v124, v132, v133
	v_cvt_pk_bf16_f32 v125, v134, v135
	v_cvt_pk_bf16_f32 v126, v136, v137
	v_cvt_pk_bf16_f32 v127, v138, v139
	v_cvt_pk_bf16_f32 v128, v140, v141
	v_cvt_pk_bf16_f32 v129, v142, v143
	v_cvt_pk_bf16_f32 v130, v144, v145
	v_cvt_pk_bf16_f32 v131, v146, v147
	v_lshlrev_b32_e32 v132, 16, v234
	v_and_b32_e32 v133, 0xffff0000, v234
	v_lshlrev_b32_e32 v134, 16, v235
	v_and_b32_e32 v135, 0xffff0000, v235
	v_lshlrev_b32_e32 v136, 16, v236
	v_and_b32_e32 v137, 0xffff0000, v236
	v_lshlrev_b32_e32 v138, 16, v237
	v_and_b32_e32 v139, 0xffff0000, v237
	v_lshlrev_b32_e32 v140, 16, v238
	v_and_b32_e32 v141, 0xffff0000, v238
	v_lshlrev_b32_e32 v142, 16, v239
	v_and_b32_e32 v143, 0xffff0000, v239
	v_lshlrev_b32_e32 v144, 16, v240
	v_and_b32_e32 v145, 0xffff0000, v240
	v_lshlrev_b32_e32 v146, 16, v241
	v_and_b32_e32 v147, 0xffff0000, v241
	v_lshlrev_b32_e32 v148, 16, v242
	v_and_b32_e32 v149, 0xffff0000, v242
	v_lshlrev_b32_e32 v150, 16, v243
	v_and_b32_e32 v151, 0xffff0000, v243
	v_lshlrev_b32_e32 v152, 16, v244
	v_and_b32_e32 v153, 0xffff0000, v244
	v_lshlrev_b32_e32 v154, 16, v245
	v_and_b32_e32 v155, 0xffff0000, v245
	v_lshlrev_b32_e32 v156, 16, v246
	v_and_b32_e32 v157, 0xffff0000, v246
	v_lshlrev_b32_e32 v158, 16, v247
	v_and_b32_e32 v159, 0xffff0000, v247
	v_lshlrev_b32_e32 v160, 16, v248
	v_and_b32_e32 v161, 0xffff0000, v248
	v_lshlrev_b32_e32 v162, 16, v249
	v_and_b32_e32 v163, 0xffff0000, v249
	v_mul_f32_e32 v56, v132, v132
	v_fmac_f32_e32 v56, v133, v133
	v_fmac_f32_e32 v56, v134, v134
	v_fmac_f32_e32 v56, v135, v135
	v_fmac_f32_e32 v56, v136, v136
	v_fmac_f32_e32 v56, v137, v137
	v_fmac_f32_e32 v56, v138, v138
	v_fmac_f32_e32 v56, v139, v139
	v_fmac_f32_e32 v56, v140, v140
	v_fmac_f32_e32 v56, v141, v141
	v_fmac_f32_e32 v56, v142, v142
	v_fmac_f32_e32 v56, v143, v143
	v_fmac_f32_e32 v56, v144, v144
	v_fmac_f32_e32 v56, v145, v145
	v_fmac_f32_e32 v56, v146, v146
	v_fmac_f32_e32 v56, v147, v147
	v_fmac_f32_e32 v56, v148, v148
	v_fmac_f32_e32 v56, v149, v149
	v_fmac_f32_e32 v56, v150, v150
	v_fmac_f32_e32 v56, v151, v151
	v_fmac_f32_e32 v56, v152, v152
	v_fmac_f32_e32 v56, v153, v153
	v_fmac_f32_e32 v56, v154, v154
	v_fmac_f32_e32 v56, v155, v155
	v_fmac_f32_e32 v56, v156, v156
	v_fmac_f32_e32 v56, v157, v157
	v_fmac_f32_e32 v56, v158, v158
	v_fmac_f32_e32 v56, v159, v159
	v_fmac_f32_e32 v56, v160, v160
	v_fmac_f32_e32 v56, v161, v161
	v_fmac_f32_e32 v56, v162, v162
	v_fmac_f32_e32 v56, v163, v163
	v_mov_b32_e32 v57, v56
	s_nop 1
	v_permlane32_swap_b32_e32 v57, v56
	v_add_f32_e32 v56, v57, v56
	v_fmamk_f32 v56, v56, 0x3c800000, v174
	v_rsq_f32_e32 v56, v56
	v_mov_b32_e32 v58, 0x3e38aa3b
	v_pk_mul_f32 v[132:133], v[132:133], v[56:57] op_sel_hi:[1,0]
	v_pk_mul_f32 v[134:135], v[134:135], v[56:57] op_sel_hi:[1,0]
	v_pk_mul_f32 v[136:137], v[136:137], v[56:57] op_sel_hi:[1,0]
	v_pk_mul_f32 v[138:139], v[138:139], v[56:57] op_sel_hi:[1,0]
	v_pk_mul_f32 v[140:141], v[140:141], v[56:57] op_sel_hi:[1,0]
	v_pk_mul_f32 v[142:143], v[142:143], v[56:57] op_sel_hi:[1,0]
	v_pk_mul_f32 v[144:145], v[144:145], v[56:57] op_sel_hi:[1,0]
	v_pk_mul_f32 v[146:147], v[146:147], v[56:57] op_sel_hi:[1,0]
	v_pk_mul_f32 v[148:149], v[148:149], v[56:57] op_sel_hi:[1,0]
	v_pk_mul_f32 v[150:151], v[150:151], v[56:57] op_sel_hi:[1,0]
	v_pk_mul_f32 v[152:153], v[152:153], v[56:57] op_sel_hi:[1,0]
	v_pk_mul_f32 v[154:155], v[154:155], v[56:57] op_sel_hi:[1,0]
	v_pk_mul_f32 v[156:157], v[156:157], v[56:57] op_sel_hi:[1,0]
	v_pk_mul_f32 v[158:159], v[158:159], v[56:57] op_sel_hi:[1,0]
	v_pk_mul_f32 v[160:161], v[160:161], v[56:57] op_sel_hi:[1,0]
	v_pk_mul_f32 v[162:163], v[162:163], v[56:57] op_sel_hi:[1,0]
	v_pk_mul_f32 v[132:133], v[132:133], v[16:17]
	v_pk_mul_f32 v[134:135], v[134:135], v[18:19]
	v_pk_mul_f32 v[136:137], v[136:137], v[20:21]
	v_pk_mul_f32 v[138:139], v[138:139], v[22:23]
	v_pk_mul_f32 v[140:141], v[140:141], v[24:25]
	v_pk_mul_f32 v[142:143], v[142:143], v[26:27]
	v_pk_mul_f32 v[144:145], v[144:145], v[28:29]
	v_pk_mul_f32 v[146:147], v[146:147], v[30:31]
	v_pk_mul_f32 v[148:149], v[148:149], v[32:33]
	v_pk_mul_f32 v[150:151], v[150:151], v[34:35]
	v_pk_mul_f32 v[152:153], v[152:153], v[36:37]
	v_pk_mul_f32 v[154:155], v[154:155], v[38:39]
	v_pk_mul_f32 v[156:157], v[156:157], v[40:41]
	v_pk_mul_f32 v[158:159], v[158:159], v[42:43]
	v_pk_mul_f32 v[160:161], v[160:161], v[44:45]
	v_pk_mul_f32 v[162:163], v[162:163], v[46:47]
	v_mov_b32_e32 v68, v132
	v_mov_b32_e32 v69, v132
	s_nop 1
	v_permlane32_swap_b32_e32 v68, v69
	v_cndmask_b32_e64 v60, v69, v68, s[66:67]
	v_mov_b32_e32 v68, v133
	v_mov_b32_e32 v69, v133
	s_nop 1
	v_permlane32_swap_b32_e32 v68, v69
	v_cndmask_b32_e64 v61, v69, v68, s[66:67]
	v_mov_b32_e32 v68, v134
	v_mov_b32_e32 v69, v134
	s_nop 1
	v_permlane32_swap_b32_e32 v68, v69
	v_cndmask_b32_e64 v62, v69, v68, s[66:67]
	v_mov_b32_e32 v68, v135
	v_mov_b32_e32 v69, v135
	s_nop 1
	v_permlane32_swap_b32_e32 v68, v69
	v_cndmask_b32_e64 v63, v69, v68, s[66:67]
	v_mov_b32_e32 v68, v136
	v_mov_b32_e32 v69, v136
	s_nop 1
	v_permlane32_swap_b32_e32 v68, v69
	v_cndmask_b32_e64 v64, v69, v68, s[66:67]
	v_mov_b32_e32 v68, v137
	v_mov_b32_e32 v69, v137
	s_nop 1
	v_permlane32_swap_b32_e32 v68, v69
	v_cndmask_b32_e64 v65, v69, v68, s[66:67]
	v_mov_b32_e32 v68, v138
	v_mov_b32_e32 v69, v138
	s_nop 1
	v_permlane32_swap_b32_e32 v68, v69
	v_cndmask_b32_e64 v66, v69, v68, s[66:67]
	v_mov_b32_e32 v68, v139
	v_mov_b32_e32 v69, v139
	s_nop 1
	v_permlane32_swap_b32_e32 v68, v69
	v_cndmask_b32_e64 v67, v69, v68, s[66:67]
	v_mul_f32_e32 v60, v60, v97
	v_mul_f32_e32 v61, v61, v99
	v_mul_f32_e32 v62, v62, v101
	v_mul_f32_e32 v63, v63, v103
	v_mul_f32_e32 v64, v64, v105
	v_mul_f32_e32 v65, v65, v107
	v_mul_f32_e32 v66, v66, v109
	v_mul_f32_e32 v67, v67, v111
	v_cndmask_b32_e64 v60, -v60, v60, s[66:67]
	v_cndmask_b32_e64 v61, -v61, v61, s[66:67]
	v_cndmask_b32_e64 v62, -v62, v62, s[66:67]
	v_cndmask_b32_e64 v63, -v63, v63, s[66:67]
	v_cndmask_b32_e64 v64, -v64, v64, s[66:67]
	v_cndmask_b32_e64 v65, -v65, v65, s[66:67]
	v_cndmask_b32_e64 v66, -v66, v66, s[66:67]
	v_cndmask_b32_e64 v67, -v67, v67, s[66:67]
	v_fma_f32 v132, v132, v96, v60
	v_fma_f32 v133, v133, v98, v61
	v_fma_f32 v134, v134, v100, v62
	v_fma_f32 v135, v135, v102, v63
	v_fma_f32 v136, v136, v104, v64
	v_fma_f32 v137, v137, v106, v65
	v_fma_f32 v138, v138, v108, v66
	v_fma_f32 v139, v139, v110, v67
	v_pk_mul_f32 v[132:133], v[132:133], v[58:59] op_sel_hi:[1,0]
	v_pk_mul_f32 v[134:135], v[134:135], v[58:59] op_sel_hi:[1,0]
	v_pk_mul_f32 v[136:137], v[136:137], v[58:59] op_sel_hi:[1,0]
	v_pk_mul_f32 v[138:139], v[138:139], v[58:59] op_sel_hi:[1,0]
	v_pk_mul_f32 v[140:141], v[140:141], v[58:59] op_sel_hi:[1,0]
	v_pk_mul_f32 v[142:143], v[142:143], v[58:59] op_sel_hi:[1,0]
	v_pk_mul_f32 v[144:145], v[144:145], v[58:59] op_sel_hi:[1,0]
	v_pk_mul_f32 v[146:147], v[146:147], v[58:59] op_sel_hi:[1,0]
	v_pk_mul_f32 v[148:149], v[148:149], v[58:59] op_sel_hi:[1,0]
	v_pk_mul_f32 v[150:151], v[150:151], v[58:59] op_sel_hi:[1,0]
	v_pk_mul_f32 v[152:153], v[152:153], v[58:59] op_sel_hi:[1,0]
	v_pk_mul_f32 v[154:155], v[154:155], v[58:59] op_sel_hi:[1,0]
	v_pk_mul_f32 v[156:157], v[156:157], v[58:59] op_sel_hi:[1,0]
	v_pk_mul_f32 v[158:159], v[158:159], v[58:59] op_sel_hi:[1,0]
	v_pk_mul_f32 v[160:161], v[160:161], v[58:59] op_sel_hi:[1,0]
	v_pk_mul_f32 v[162:163], v[162:163], v[58:59] op_sel_hi:[1,0]
	v_cvt_pk_bf16_f32 v132, v132, v133
	v_cvt_pk_bf16_f32 v133, v134, v135
	v_cvt_pk_bf16_f32 v134, v136, v137
	v_cvt_pk_bf16_f32 v135, v138, v139
	v_cvt_pk_bf16_f32 v136, v140, v141
	v_cvt_pk_bf16_f32 v137, v142, v143
	v_cvt_pk_bf16_f32 v138, v144, v145
	v_cvt_pk_bf16_f32 v139, v146, v147
	v_cvt_pk_bf16_f32 v140, v148, v149
	v_cvt_pk_bf16_f32 v141, v150, v151
	v_cvt_pk_bf16_f32 v142, v152, v153
	v_cvt_pk_bf16_f32 v143, v154, v155
	v_cvt_pk_bf16_f32 v144, v156, v157
	v_cvt_pk_bf16_f32 v145, v158, v159
	v_cvt_pk_bf16_f32 v146, v160, v161
	v_cvt_pk_bf16_f32 v147, v162, v163
	v_mov_b32_e32 v212, s11
	v_mul_f32_e32 v173, 0x3fb8aa3b, v212
	v_mul_f32_e32 v251, 0x3fb8aa3b, v212
	v_cndmask_b32_e64 v6, 1.0, 0, s[66:67]
	v_cndmask_b32_e64 v3, 1.0, 0, s[66:67]
	v_mov_b32_e32 v16, 0
	v_mov_b32_e32 v17, 0
	v_mov_b32_e32 v18, 0
	v_mov_b32_e32 v19, 0
	v_mov_b32_e32 v20, 0
	v_mov_b32_e32 v21, 0
	v_mov_b32_e32 v22, 0
	v_mov_b32_e32 v23, 0
	v_mov_b32_e32 v24, 0
	v_mov_b32_e32 v25, 0
	v_mov_b32_e32 v26, 0
	v_mov_b32_e32 v27, 0
	v_mov_b32_e32 v28, 0
	v_mov_b32_e32 v29, 0
	v_mov_b32_e32 v30, 0
	v_mov_b32_e32 v31, 0
	v_mov_b32_e32 v32, 0
	v_mov_b32_e32 v33, 0
	v_mov_b32_e32 v34, 0
	v_mov_b32_e32 v35, 0
	v_mov_b32_e32 v36, 0
	v_mov_b32_e32 v37, 0
	v_mov_b32_e32 v38, 0
	v_mov_b32_e32 v39, 0
	v_mov_b32_e32 v40, 0
	v_mov_b32_e32 v41, 0
	v_mov_b32_e32 v42, 0
	v_mov_b32_e32 v43, 0
	v_mov_b32_e32 v44, 0
	v_mov_b32_e32 v45, 0
	v_mov_b32_e32 v46, 0
	v_mov_b32_e32 v47, 0
	v_mov_b32_e32 v48, 0
	v_mov_b32_e32 v49, 0
	v_mov_b32_e32 v50, 0
	v_mov_b32_e32 v51, 0
	v_mov_b32_e32 v52, 0
	v_mov_b32_e32 v53, 0
	v_mov_b32_e32 v54, 0
	v_mov_b32_e32 v55, 0
	v_mov_b32_e32 v56, 0
	v_mov_b32_e32 v57, 0
	v_mov_b32_e32 v58, 0
	v_mov_b32_e32 v59, 0
	v_mov_b32_e32 v60, 0
	v_mov_b32_e32 v61, 0
	v_mov_b32_e32 v62, 0
	v_mov_b32_e32 v63, 0
	v_mov_b32_e32 v64, 0
	v_mov_b32_e32 v65, 0
	v_mov_b32_e32 v66, 0
	v_mov_b32_e32 v67, 0
	v_mov_b32_e32 v68, 0
	v_mov_b32_e32 v69, 0
	v_mov_b32_e32 v70, 0
	v_mov_b32_e32 v71, 0
	v_mov_b32_e32 v72, 0
	v_mov_b32_e32 v73, 0
	v_mov_b32_e32 v74, 0
	v_mov_b32_e32 v75, 0
	v_mov_b32_e32 v76, 0
	v_mov_b32_e32 v77, 0
	v_mov_b32_e32 v78, 0
	v_mov_b32_e32 v79, 0
	s_barrier
	s_cmp_eq_u32 s58, 3
	s_cbranch_scc1 .Lat_nopf_11
	global_load_dwordx4 v[192:195], v10, s[86:87] offset:0
	global_load_dwordx4 v[196:199], v10, s[86:87] offset:32
	global_load_dwordx4 v[200:203], v10, s[86:87] offset:64
	global_load_dwordx4 v[204:207], v10, s[86:87] offset:96
	global_load_dwordx4 v[234:237], v11, s[86:87] offset:0
	global_load_dwordx4 v[238:241], v11, s[86:87] offset:32
	global_load_dwordx4 v[242:245], v11, s[86:87] offset:64
	global_load_dwordx4 v[246:249], v11, s[86:87] offset:96
	s_add_u32 s4, s7, 128
	v_add_u32_e32 v217, s4, v7
	v_add_u32_e32 v212, 256, v217
	v_max_i32_e32 v212, 0, v212
	v_min_u32_e32 v212, 0x1fff, v212
	v_mul_lo_u32 v172, v212, s60
	v_add_u32_e32 v172, v172, v4
	global_load_dwordx4 v[164:167], v172, s[38:39] offset:2048
	global_load_dwordx4 v[168:171], v172, s[38:39] offset:2560
	v_add_u32_e32 v212, 320, v217
	v_max_i32_e32 v212, 0, v212
	v_min_u32_e32 v212, 0x1fff, v212
	v_mul_lo_u32 v172, v212, s60
	v_add_u32_e32 v172, v172, v4
	global_load_dwordx4 v[208:211], v172, s[38:39] offset:2048
	global_load_dwordx4 v[222:225], v172, s[38:39] offset:2560
.Lat_nopf_11:
	s_lshl_b32 s4, s57, 5
	s_add_u32 s4, s4, s70
	s_add_u32 s4, s4, s83
	s_and_b32 s69, s4, 0x1ff
	s_mul_i32 s4, s69, 0x90
	v_add_u32_e32 v216, s4, v8
	v_add_u32_e32 v217, s4, v9
	ds_read_b128 v[148:151], v216 offset:0
	ds_read_b128 v[152:155], v216 offset:32
	ds_read_b128 v[156:159], v216 offset:64
	ds_read_b128 v[160:163], v216 offset:96
	ds_read_b64_tr_b16 v[176:177], v217 offset:0
	ds_read_b64_tr_b16 v[178:179], v217 offset:1152
	ds_read_b64_tr_b16 v[180:181], v217 offset:2304
	ds_read_b64_tr_b16 v[182:183], v217 offset:3456
	ds_read_b64_tr_b16 v[184:185], v217 offset:64
	ds_read_b64_tr_b16 v[186:187], v217 offset:1216
	ds_read_b64_tr_b16 v[188:189], v217 offset:2368
	ds_read_b64_tr_b16 v[190:191], v217 offset:3520
.Lat_jloop_12:
	s_cmp_eq_u32 s57, 9
	s_cbranch_scc1 .Lat_t1only_14
	s_cmp_eq_u32 s57, 0
	s_cbranch_scc1 .Lat_t0only_15
	s_waitcnt lgkmcnt(8)
	v_mfma_f32_32x32x16_bf16 v[80:95], v[148:151], v[116:119], 0
	v_mfma_f32_32x32x16_bf16 v[80:95], v[152:155], v[120:123], v[80:95]
	v_mfma_f32_32x32x16_bf16 v[80:95], v[156:159], v[124:127], v[80:95]
	v_mfma_f32_32x32x16_bf16 v[80:95], v[160:163], v[128:131], v[80:95]
	v_mfma_f32_32x32x16_bf16 v[96:111], v[148:151], v[132:135], 0
	v_mfma_f32_32x32x16_bf16 v[96:111], v[152:155], v[136:139], v[96:111]
	s_add_u32 s4, s69, 32
	s_and_b32 s84, s4, 0x1ff
	s_mul_i32 s4, s84, 0x90
	v_add_u32_e32 v216, s4, v8
	v_add_u32_e32 v217, s4, v9
	s_nop 6
	s_cmp_eq_u32 s57, 0
	s_cbranch_scc0 .Lat_nomask_16
	v_cmp_lt_i32_e64 s[74:75], 0, v15
	v_cmp_lt_i32_e64 s[76:77], 1, v15
	v_cmp_lt_i32_e64 s[78:79], 2, v15
	v_cmp_lt_i32_e64 s[80:81], 3, v15
	v_cndmask_b32_e64 v80, v80, v232, s[74:75]
	v_cndmask_b32_e64 v81, v81, v232, s[76:77]
	v_cndmask_b32_e64 v82, v82, v232, s[78:79]
	v_cndmask_b32_e64 v83, v83, v232, s[80:81]
	v_cmp_lt_i32_e64 s[74:75], 8, v15
	v_cmp_lt_i32_e64 s[76:77], 9, v15
	v_cmp_lt_i32_e64 s[78:79], 10, v15
	v_cmp_lt_i32_e64 s[80:81], 11, v15
	v_cndmask_b32_e64 v84, v84, v232, s[74:75]
	v_cndmask_b32_e64 v85, v85, v232, s[76:77]
	v_cndmask_b32_e64 v86, v86, v232, s[78:79]
	v_cndmask_b32_e64 v87, v87, v232, s[80:81]
	v_cmp_lt_i32_e64 s[74:75], 16, v15
	v_cmp_lt_i32_e64 s[76:77], 17, v15
	v_cmp_lt_i32_e64 s[78:79], 18, v15
	v_cmp_lt_i32_e64 s[80:81], 19, v15
	v_cndmask_b32_e64 v88, v88, v232, s[74:75]
	v_cndmask_b32_e64 v89, v89, v232, s[76:77]
	v_cndmask_b32_e64 v90, v90, v232, s[78:79]
	v_cndmask_b32_e64 v91, v91, v232, s[80:81]
	v_cmp_lt_i32_e64 s[74:75], 24, v15
	v_cmp_lt_i32_e64 s[76:77], 25, v15
	v_cmp_lt_i32_e64 s[78:79], 26, v15
	v_cmp_lt_i32_e64 s[80:81], 27, v15
	v_cndmask_b32_e64 v92, v92, v232, s[74:75]
	v_cndmask_b32_e64 v93, v93, v232, s[76:77]
	v_cndmask_b32_e64 v94, v94, v232, s[78:79]
	v_cndmask_b32_e64 v95, v95, v232, s[80:81]

.Lat_nomask_17:
	v_max3_f32 v212, v80, v81, v82
	v_max3_f32 v250, v83, v84, v85
	v_max3_f32 v212, v212, v86, v87
	v_max3_f32 v250, v250, v88, v89
	v_max3_f32 v212, v212, v90, v91
	v_max3_f32 v250, v250, v92, v93
	v_max3_f32 v212, v212, v94, v95
	v_max_f32_e32 v212, v212, v250
	v_mov_b32_e32 v250, v212
	s_nop 1
	v_permlane32_swap_b32_e32 v212, v250
	v_max_f32_e32 v212, v212, v250
	v_sub_f32_e32 v212, v212, v173
	v_cmp_lt_f32_e32 vcc, 0x41000000, v212
	s_cbranch_vccz .Lat_nors_18
	v_max_f32_e32 v212, 0, v212
	v_exp_f32_e64 v172, -v212
	v_add_f32_e32 v173, v173, v212
	v_mul_f32_e32 v6, v6, v172
	v_mul_f32_e32 v16, v16, v172
	v_mul_f32_e32 v17, v17, v172
	v_mul_f32_e32 v18, v18, v172
	v_mul_f32_e32 v19, v19, v172
	v_mul_f32_e32 v20, v20, v172
	v_mul_f32_e32 v21, v21, v172
	v_mul_f32_e32 v22, v22, v172
	v_mul_f32_e32 v23, v23, v172
	v_mul_f32_e32 v24, v24, v172
	v_mul_f32_e32 v25, v25, v172
	v_mul_f32_e32 v26, v26, v172
	v_mul_f32_e32 v27, v27, v172
	v_mul_f32_e32 v28, v28, v172
	v_mul_f32_e32 v29, v29, v172
	v_mul_f32_e32 v30, v30, v172
	v_mul_f32_e32 v31, v31, v172
	v_mul_f32_e32 v32, v32, v172
	v_mul_f32_e32 v33, v33, v172
	v_mul_f32_e32 v34, v34, v172
	v_mul_f32_e32 v35, v35, v172
	v_mul_f32_e32 v36, v36, v172
	v_mul_f32_e32 v37, v37, v172
	v_mul_f32_e32 v38, v38, v172
	v_mul_f32_e32 v39, v39, v172
	v_mul_f32_e32 v40, v40, v172
	v_mul_f32_e32 v41, v41, v172
	v_mul_f32_e32 v42, v42, v172
	v_mul_f32_e32 v43, v43, v172
	v_mul_f32_e32 v44, v44, v172
	v_mul_f32_e32 v45, v45, v172
	v_mul_f32_e32 v46, v46, v172
	v_mul_f32_e32 v47, v47, v172
.Lat_nors_18:
	v_sub_f32_e32 v80, v80, v173
	v_sub_f32_e32 v81, v81, v173
	v_sub_f32_e32 v82, v82, v173
	v_sub_f32_e32 v83, v83, v173
	v_sub_f32_e32 v84, v84, v173
	v_sub_f32_e32 v85, v85, v173
	v_mfma_f32_32x32x16_bf16 v[96:111], v[156:159], v[140:143], v[96:111]
	v_sub_f32_e32 v86, v86, v173
	v_sub_f32_e32 v87, v87, v173
	v_sub_f32_e32 v88, v88, v173
	v_sub_f32_e32 v89, v89, v173
	v_sub_f32_e32 v90, v90, v173
	v_sub_f32_e32 v91, v91, v173
	v_sub_f32_e32 v92, v92, v173
	v_sub_f32_e32 v93, v93, v173
	v_mfma_f32_32x32x16_bf16 v[96:111], v[160:163], v[144:147], v[96:111]
	ds_read_b128 v[148:151], v216 offset:0
	ds_read_b128 v[152:155], v216 offset:32
	ds_read_b128 v[156:159], v216 offset:64
	ds_read_b128 v[160:163], v216 offset:96
	v_sub_f32_e32 v94, v94, v173
	v_sub_f32_e32 v95, v95, v173
	v_exp_f32_e32 v80, v80
	v_exp_f32_e32 v81, v81
	v_exp_f32_e32 v82, v82
	v_exp_f32_e32 v83, v83
	v_exp_f32_e32 v84, v84
	v_exp_f32_e32 v85, v85
	v_exp_f32_e32 v86, v86
	v_exp_f32_e32 v87, v87
	v_exp_f32_e32 v88, v88
	v_exp_f32_e32 v89, v89
	v_exp_f32_e32 v90, v90
	v_exp_f32_e32 v91, v91
	v_exp_f32_e32 v92, v92
	v_exp_f32_e32 v93, v93
	v_exp_f32_e32 v94, v94
	v_exp_f32_e32 v95, v95
	v_add_f32_e32 v212, v80, v81
	v_add_f32_e32 v250, v82, v83
	v_add_f32_e32 v212, v212, v84
	v_add_f32_e32 v250, v250, v85
	v_add_f32_e32 v212, v212, v86
	v_add_f32_e32 v250, v250, v87
	v_add_f32_e32 v212, v212, v88
	v_add_f32_e32 v250, v250, v89
	v_add_f32_e32 v212, v212, v90
	v_add_f32_e32 v250, v250, v91
	v_add_f32_e32 v212, v212, v92
	v_add_f32_e32 v250, v250, v93
	v_add_f32_e32 v212, v212, v94
	v_add_f32_e32 v250, v250, v95
	v_add_f32_e32 v212, v212, v250
	v_add_f32_e32 v6, v6, v212
	v_cvt_pk_bf16_f32 v80, v80, v81
	v_cvt_pk_bf16_f32 v81, v82, v83
	v_cvt_pk_bf16_f32 v82, v84, v85
	v_cvt_pk_bf16_f32 v83, v86, v87
	v_cvt_pk_bf16_f32 v84, v88, v89
	v_cvt_pk_bf16_f32 v85, v90, v91
	v_cvt_pk_bf16_f32 v86, v92, v93
	v_cvt_pk_bf16_f32 v87, v94, v95
	s_cmp_eq_u32 s57, 1
	s_cbranch_scc0 .Lat_nomask_19
	v_cmp_lt_i32_e64 s[74:75], 0, v15
	v_cmp_lt_i32_e64 s[76:77], 1, v15
	v_cmp_lt_i32_e64 s[78:79], 2, v15
	v_cmp_lt_i32_e64 s[80:81], 3, v15
	v_cndmask_b32_e64 v96, v96, v232, s[74:75]
	v_cndmask_b32_e64 v97, v97, v232, s[76:77]
	v_cndmask_b32_e64 v98, v98, v232, s[78:79]
	v_cndmask_b32_e64 v99, v99, v232, s[80:81]
	v_cmp_lt_i32_e64 s[74:75], 8, v15
	v_cmp_lt_i32_e64 s[76:77], 9, v15
	v_cmp_lt_i32_e64 s[78:79], 10, v15
	v_cmp_lt_i32_e64 s[80:81], 11, v15
	v_cndmask_b32_e64 v100, v100, v232, s[74:75]
	v_cndmask_b32_e64 v101, v101, v232, s[76:77]
	v_cndmask_b32_e64 v102, v102, v232, s[78:79]
	v_cndmask_b32_e64 v103, v103, v232, s[80:81]
	v_cmp_lt_i32_e64 s[74:75], 16, v15
	v_cmp_lt_i32_e64 s[76:77], 17, v15
	v_cmp_lt_i32_e64 s[78:79], 18, v15
	v_cmp_lt_i32_e64 s[80:81], 19, v15
	v_cndmask_b32_e64 v104, v104, v232, s[74:75]
	v_cndmask_b32_e64 v105, v105, v232, s[76:77]
	v_cndmask_b32_e64 v106, v106, v232, s[78:79]
	v_cndmask_b32_e64 v107, v107, v232, s[80:81]
	v_cmp_lt_i32_e64 s[74:75], 24, v15
	v_cmp_lt_i32_e64 s[76:77], 25, v15
	v_cmp_lt_i32_e64 s[78:79], 26, v15
	v_cmp_lt_i32_e64 s[80:81], 27, v15
	v_cndmask_b32_e64 v108, v108, v232, s[74:75]
	v_cndmask_b32_e64 v109, v109, v232, s[76:77]
	v_cndmask_b32_e64 v110, v110, v232, s[78:79]
	v_cndmask_b32_e64 v111, v111, v232, s[80:81]

.Lat_nomask_20:
	s_waitcnt lgkmcnt(4)
	v_mfma_f32_32x32x16_bf16 v[16:31], v[176:179], v[80:83], v[16:31]
	v_max3_f32 v212, v96, v97, v98
	v_max3_f32 v250, v99, v100, v101
	v_max3_f32 v212, v212, v102, v103
	v_max3_f32 v250, v250, v104, v105
	v_max3_f32 v212, v212, v106, v107
	v_max3_f32 v250, v250, v108, v109
	v_max3_f32 v212, v212, v110, v111
	v_max_f32_e32 v212, v212, v250
	v_mfma_f32_32x32x16_bf16 v[32:47], v[184:187], v[80:83], v[32:47]
	v_mov_b32_e32 v250, v212
	s_nop 1
	v_permlane32_swap_b32_e32 v212, v250
	v_max_f32_e32 v212, v212, v250
	v_sub_f32_e32 v212, v212, v251
	v_cmp_lt_f32_e32 vcc, 0x41000000, v212
	s_cbranch_vccz .Lat_nors_21
	v_max_f32_e32 v212, 0, v212
	v_exp_f32_e64 v172, -v212
	v_add_f32_e32 v251, v251, v212
	v_mul_f32_e32 v3, v3, v172
	v_mul_f32_e32 v48, v48, v172
	v_mul_f32_e32 v49, v49, v172
	v_mul_f32_e32 v50, v50, v172
	v_mul_f32_e32 v51, v51, v172
	v_mul_f32_e32 v52, v52, v172
	v_mul_f32_e32 v53, v53, v172
	v_mul_f32_e32 v54, v54, v172
	v_mul_f32_e32 v55, v55, v172
	v_mul_f32_e32 v56, v56, v172
	v_mul_f32_e32 v57, v57, v172
	v_mul_f32_e32 v58, v58, v172
	v_mul_f32_e32 v59, v59, v172
	v_mul_f32_e32 v60, v60, v172
	v_mul_f32_e32 v61, v61, v172
	v_mul_f32_e32 v62, v62, v172
	v_mul_f32_e32 v63, v63, v172
	v_mul_f32_e32 v64, v64, v172
	v_mul_f32_e32 v65, v65, v172
	v_mul_f32_e32 v66, v66, v172
	v_mul_f32_e32 v67, v67, v172
	v_mul_f32_e32 v68, v68, v172
	v_mul_f32_e32 v69, v69, v172
	v_mul_f32_e32 v70, v70, v172
	v_mul_f32_e32 v71, v71, v172
	v_mul_f32_e32 v72, v72, v172
	v_mul_f32_e32 v73, v73, v172
	v_mul_f32_e32 v74, v74, v172
	v_mul_f32_e32 v75, v75, v172
	v_mul_f32_e32 v76, v76, v172
	v_mul_f32_e32 v77, v77, v172
	v_mul_f32_e32 v78, v78, v172
	v_mul_f32_e32 v79, v79, v172
.Lat_nors_21:
	v_sub_f32_e32 v96, v96, v251
	v_sub_f32_e32 v97, v97, v251
	v_sub_f32_e32 v98, v98, v251
	v_sub_f32_e32 v99, v99, v251
	v_sub_f32_e32 v100, v100, v251
	v_sub_f32_e32 v101, v101, v251
	v_mfma_f32_32x32x16_bf16 v[16:31], v[180:183], v[84:87], v[16:31]
	v_sub_f32_e32 v102, v102, v251
	v_sub_f32_e32 v103, v103, v251
	v_sub_f32_e32 v104, v104, v251
	v_sub_f32_e32 v105, v105, v251
	v_sub_f32_e32 v106, v106, v251
	v_sub_f32_e32 v107, v107, v251
	v_sub_f32_e32 v108, v108, v251
	v_sub_f32_e32 v109, v109, v251
	v_mfma_f32_32x32x16_bf16 v[32:47], v[188:191], v[84:87], v[32:47]
	v_sub_f32_e32 v110, v110, v251
	v_sub_f32_e32 v111, v111, v251
	v_exp_f32_e32 v96, v96
	v_exp_f32_e32 v97, v97
	v_exp_f32_e32 v98, v98
	v_exp_f32_e32 v99, v99
	v_exp_f32_e32 v100, v100
	v_exp_f32_e32 v101, v101
	v_exp_f32_e32 v102, v102
	v_exp_f32_e32 v103, v103
	v_exp_f32_e32 v104, v104
	v_exp_f32_e32 v105, v105
	v_exp_f32_e32 v106, v106
	v_exp_f32_e32 v107, v107
	v_exp_f32_e32 v108, v108
	v_exp_f32_e32 v109, v109
	v_exp_f32_e32 v110, v110
	v_exp_f32_e32 v111, v111
	v_add_f32_e32 v212, v96, v97
	v_add_f32_e32 v250, v98, v99
	v_add_f32_e32 v212, v212, v100
	v_add_f32_e32 v250, v250, v101
	v_add_f32_e32 v212, v212, v102
	v_add_f32_e32 v250, v250, v103
	v_add_f32_e32 v212, v212, v104
	v_add_f32_e32 v250, v250, v105
	v_add_f32_e32 v212, v212, v106
	v_add_f32_e32 v250, v250, v107
	v_add_f32_e32 v212, v212, v108
	v_add_f32_e32 v250, v250, v109
	v_add_f32_e32 v212, v212, v110
	v_add_f32_e32 v250, v250, v111
	v_add_f32_e32 v212, v212, v250
	v_add_f32_e32 v3, v3, v212
	v_cvt_pk_bf16_f32 v96, v96, v97
	v_cvt_pk_bf16_f32 v97, v98, v99
	v_cvt_pk_bf16_f32 v98, v100, v101
	v_cvt_pk_bf16_f32 v99, v102, v103
	v_cvt_pk_bf16_f32 v100, v104, v105
	v_cvt_pk_bf16_f32 v101, v106, v107
	v_cvt_pk_bf16_f32 v102, v108, v109
	v_cvt_pk_bf16_f32 v103, v110, v111
	v_mfma_f32_32x32x16_bf16 v[48:63], v[176:179], v[96:99], v[48:63]
	v_mfma_f32_32x32x16_bf16 v[64:79], v[184:187], v[96:99], v[64:79]
	v_mfma_f32_32x32x16_bf16 v[48:63], v[180:183], v[100:103], v[48:63]
	v_mfma_f32_32x32x16_bf16 v[64:79], v[188:191], v[100:103], v[64:79]
	ds_read_b64_tr_b16 v[176:177], v217 offset:0
	ds_read_b64_tr_b16 v[178:179], v217 offset:1152
	ds_read_b64_tr_b16 v[180:181], v217 offset:2304
	ds_read_b64_tr_b16 v[182:183], v217 offset:3456
	ds_read_b64_tr_b16 v[184:185], v217 offset:64
	ds_read_b64_tr_b16 v[186:187], v217 offset:1216
	ds_read_b64_tr_b16 v[188:189], v217 offset:2368
	ds_read_b64_tr_b16 v[190:191], v217 offset:3520
	s_branch .Lat_jnext_13
.Lat_t0only_15:
	s_waitcnt lgkmcnt(8)
	v_mfma_f32_32x32x16_bf16 v[80:95], v[148:151], v[116:119], 0
	v_mfma_f32_32x32x16_bf16 v[80:95], v[152:155], v[120:123], v[80:95]
	v_mfma_f32_32x32x16_bf16 v[80:95], v[156:159], v[124:127], v[80:95]
	v_mfma_f32_32x32x16_bf16 v[80:95], v[160:163], v[128:131], v[80:95]
	s_add_u32 s4, s69, 32
	s_and_b32 s84, s4, 0x1ff
	s_mul_i32 s4, s84, 0x90
	v_add_u32_e32 v216, s4, v8
	v_add_u32_e32 v217, s4, v9
	ds_read_b128 v[148:151], v216 offset:0
	ds_read_b128 v[152:155], v216 offset:32
	ds_read_b128 v[156:159], v216 offset:64
	ds_read_b128 v[160:163], v216 offset:96
	s_nop 7
	s_nop 7
	s_cmp_eq_u32 s57, 0
	s_cbranch_scc0 .Lat_nomask_22
	v_cmp_lt_i32_e64 s[74:75], 0, v15
	v_cmp_lt_i32_e64 s[76:77], 1, v15
	v_cmp_lt_i32_e64 s[78:79], 2, v15
	v_cmp_lt_i32_e64 s[80:81], 3, v15
	v_cndmask_b32_e64 v80, v80, v232, s[74:75]
	v_cndmask_b32_e64 v81, v81, v232, s[76:77]
	v_cndmask_b32_e64 v82, v82, v232, s[78:79]
	v_cndmask_b32_e64 v83, v83, v232, s[80:81]
	v_cmp_lt_i32_e64 s[74:75], 8, v15
	v_cmp_lt_i32_e64 s[76:77], 9, v15
	v_cmp_lt_i32_e64 s[78:79], 10, v15
	v_cmp_lt_i32_e64 s[80:81], 11, v15
	v_cndmask_b32_e64 v84, v84, v232, s[74:75]
	v_cndmask_b32_e64 v85, v85, v232, s[76:77]
	v_cndmask_b32_e64 v86, v86, v232, s[78:79]
	v_cndmask_b32_e64 v87, v87, v232, s[80:81]
	v_cmp_lt_i32_e64 s[74:75], 16, v15
	v_cmp_lt_i32_e64 s[76:77], 17, v15
	v_cmp_lt_i32_e64 s[78:79], 18, v15
	v_cmp_lt_i32_e64 s[80:81], 19, v15
	v_cndmask_b32_e64 v88, v88, v232, s[74:75]
	v_cndmask_b32_e64 v89, v89, v232, s[76:77]
	v_cndmask_b32_e64 v90, v90, v232, s[78:79]
	v_cndmask_b32_e64 v91, v91, v232, s[80:81]
	v_cmp_lt_i32_e64 s[74:75], 24, v15
	v_cmp_lt_i32_e64 s[76:77], 25, v15
	v_cmp_lt_i32_e64 s[78:79], 26, v15
	v_cmp_lt_i32_e64 s[80:81], 27, v15
	v_cndmask_b32_e64 v92, v92, v232, s[74:75]
	v_cndmask_b32_e64 v93, v93, v232, s[76:77]
	v_cndmask_b32_e64 v94, v94, v232, s[78:79]
	v_cndmask_b32_e64 v95, v95, v232, s[80:81]

.Lat_nors_24:
	v_sub_f32_e32 v80, v80, v173
	v_sub_f32_e32 v81, v81, v173
	v_sub_f32_e32 v82, v82, v173
	v_sub_f32_e32 v83, v83, v173
	v_sub_f32_e32 v84, v84, v173
	v_sub_f32_e32 v85, v85, v173
	v_sub_f32_e32 v86, v86, v173
	v_sub_f32_e32 v87, v87, v173
	v_sub_f32_e32 v88, v88, v173
	v_sub_f32_e32 v89, v89, v173
	v_sub_f32_e32 v90, v90, v173
	v_sub_f32_e32 v91, v91, v173
	v_sub_f32_e32 v92, v92, v173
	v_sub_f32_e32 v93, v93, v173
	v_sub_f32_e32 v94, v94, v173
	v_sub_f32_e32 v95, v95, v173
	v_exp_f32_e32 v80, v80
	v_exp_f32_e32 v81, v81
	v_exp_f32_e32 v82, v82
	v_exp_f32_e32 v83, v83
	v_exp_f32_e32 v84, v84
	v_exp_f32_e32 v85, v85
	v_exp_f32_e32 v86, v86
	v_exp_f32_e32 v87, v87
	v_exp_f32_e32 v88, v88
	v_exp_f32_e32 v89, v89
	v_exp_f32_e32 v90, v90
	v_exp_f32_e32 v91, v91
	v_exp_f32_e32 v92, v92
	v_exp_f32_e32 v93, v93
	v_exp_f32_e32 v94, v94
	v_exp_f32_e32 v95, v95
	v_add_f32_e32 v212, v80, v81
	v_add_f32_e32 v250, v82, v83
	v_add_f32_e32 v212, v212, v84
	v_add_f32_e32 v250, v250, v85
	v_add_f32_e32 v212, v212, v86
	v_add_f32_e32 v250, v250, v87
	v_add_f32_e32 v212, v212, v88
	v_add_f32_e32 v250, v250, v89
	v_add_f32_e32 v212, v212, v90
	v_add_f32_e32 v250, v250, v91
	v_add_f32_e32 v212, v212, v92
	v_add_f32_e32 v250, v250, v93
	v_add_f32_e32 v212, v212, v94
	v_add_f32_e32 v250, v250, v95
	v_add_f32_e32 v212, v212, v250
	v_add_f32_e32 v6, v6, v212
	v_cvt_pk_bf16_f32 v80, v80, v81
	v_cvt_pk_bf16_f32 v81, v82, v83
	v_cvt_pk_bf16_f32 v82, v84, v85
	v_cvt_pk_bf16_f32 v83, v86, v87
	v_cvt_pk_bf16_f32 v84, v88, v89
	v_cvt_pk_bf16_f32 v85, v90, v91
	v_cvt_pk_bf16_f32 v86, v92, v93
	v_cvt_pk_bf16_f32 v87, v94, v95
	s_waitcnt lgkmcnt(4)
	v_mfma_f32_32x32x16_bf16 v[16:31], v[176:179], v[80:83], v[16:31]
	v_mfma_f32_32x32x16_bf16 v[32:47], v[184:187], v[80:83], v[32:47]
	v_mfma_f32_32x32x16_bf16 v[16:31], v[180:183], v[84:87], v[16:31]
	v_mfma_f32_32x32x16_bf16 v[32:47], v[188:191], v[84:87], v[32:47]
	ds_read_b64_tr_b16 v[176:177], v217 offset:0
	ds_read_b64_tr_b16 v[178:179], v217 offset:1152
	ds_read_b64_tr_b16 v[180:181], v217 offset:2304
	ds_read_b64_tr_b16 v[182:183], v217 offset:3456
	ds_read_b64_tr_b16 v[184:185], v217 offset:64
	ds_read_b64_tr_b16 v[186:187], v217 offset:1216
	ds_read_b64_tr_b16 v[188:189], v217 offset:2368
	ds_read_b64_tr_b16 v[190:191], v217 offset:3520
	s_branch .Lat_jnext_13
.Lat_t1only_14:
	s_waitcnt lgkmcnt(8)
	v_mfma_f32_32x32x16_bf16 v[96:111], v[148:151], v[132:135], 0
	v_mfma_f32_32x32x16_bf16 v[96:111], v[152:155], v[136:139], v[96:111]
	v_mfma_f32_32x32x16_bf16 v[96:111], v[156:159], v[140:143], v[96:111]
	v_mfma_f32_32x32x16_bf16 v[96:111], v[160:163], v[144:147], v[96:111]
	s_add_u32 s4, s69, 32
	s_and_b32 s84, s4, 0x1ff
	s_mul_i32 s4, s84, 0x90
	v_add_u32_e32 v216, s4, v8
	v_add_u32_e32 v217, s4, v9
	ds_read_b128 v[148:151], v216 offset:0
	ds_read_b128 v[152:155], v216 offset:32
	ds_read_b128 v[156:159], v216 offset:64
	ds_read_b128 v[160:163], v216 offset:96
	s_nop 7
	s_nop 7
	s_cmp_eq_u32 s57, 1
	s_cbranch_scc0 .Lat_nomask_25
	v_cmp_lt_i32_e64 s[74:75], 0, v15
	v_cmp_lt_i32_e64 s[76:77], 1, v15
	v_cmp_lt_i32_e64 s[78:79], 2, v15
	v_cmp_lt_i32_e64 s[80:81], 3, v15
	v_cndmask_b32_e64 v96, v96, v232, s[74:75]
	v_cndmask_b32_e64 v97, v97, v232, s[76:77]
	v_cndmask_b32_e64 v98, v98, v232, s[78:79]
	v_cndmask_b32_e64 v99, v99, v232, s[80:81]
	v_cmp_lt_i32_e64 s[74:75], 8, v15
	v_cmp_lt_i32_e64 s[76:77], 9, v15
	v_cmp_lt_i32_e64 s[78:79], 10, v15
	v_cmp_lt_i32_e64 s[80:81], 11, v15
	v_cndmask_b32_e64 v100, v100, v232, s[74:75]
	v_cndmask_b32_e64 v101, v101, v232, s[76:77]
	v_cndmask_b32_e64 v102, v102, v232, s[78:79]
	v_cndmask_b32_e64 v103, v103, v232, s[80:81]
	v_cmp_lt_i32_e64 s[74:75], 16, v15
	v_cmp_lt_i32_e64 s[76:77], 17, v15
	v_cmp_lt_i32_e64 s[78:79], 18, v15
	v_cmp_lt_i32_e64 s[80:81], 19, v15
	v_cndmask_b32_e64 v104, v104, v232, s[74:75]
	v_cndmask_b32_e64 v105, v105, v232, s[76:77]
	v_cndmask_b32_e64 v106, v106, v232, s[78:79]
	v_cndmask_b32_e64 v107, v107, v232, s[80:81]
	v_cmp_lt_i32_e64 s[74:75], 24, v15
	v_cmp_lt_i32_e64 s[76:77], 25, v15
	v_cmp_lt_i32_e64 s[78:79], 26, v15
	v_cmp_lt_i32_e64 s[80:81], 27, v15
	v_cndmask_b32_e64 v108, v108, v232, s[74:75]
	v_cndmask_b32_e64 v109, v109, v232, s[76:77]
	v_cndmask_b32_e64 v110, v110, v232, s[78:79]
	v_cndmask_b32_e64 v111, v111, v232, s[80:81]

.Lat_nomask_26:
	v_max3_f32 v212, v96, v97, v98
	v_max3_f32 v250, v99, v100, v101
	v_max3_f32 v212, v212, v102, v103
	v_max3_f32 v250, v250, v104, v105
	v_max3_f32 v212, v212, v106, v107
	v_max3_f32 v250, v250, v108, v109
	v_max3_f32 v212, v212, v110, v111
	v_max_f32_e32 v212, v212, v250
	v_mov_b32_e32 v250, v212
	s_nop 1
	v_permlane32_swap_b32_e32 v212, v250
	v_max_f32_e32 v212, v212, v250
	v_sub_f32_e32 v212, v212, v251
	v_cmp_lt_f32_e32 vcc, 0x41000000, v212
	s_cbranch_vccz .Lat_nors_27
	v_max_f32_e32 v212, 0, v212
	v_exp_f32_e64 v172, -v212
	v_add_f32_e32 v251, v251, v212
	v_mul_f32_e32 v3, v3, v172
	v_mul_f32_e32 v48, v48, v172
	v_mul_f32_e32 v49, v49, v172
	v_mul_f32_e32 v50, v50, v172
	v_mul_f32_e32 v51, v51, v172
	v_mul_f32_e32 v52, v52, v172
	v_mul_f32_e32 v53, v53, v172
	v_mul_f32_e32 v54, v54, v172
	v_mul_f32_e32 v55, v55, v172
	v_mul_f32_e32 v56, v56, v172
	v_mul_f32_e32 v57, v57, v172
	v_mul_f32_e32 v58, v58, v172
	v_mul_f32_e32 v59, v59, v172
	v_mul_f32_e32 v60, v60, v172
	v_mul_f32_e32 v61, v61, v172
	v_mul_f32_e32 v62, v62, v172
	v_mul_f32_e32 v63, v63, v172
	v_mul_f32_e32 v64, v64, v172
	v_mul_f32_e32 v65, v65, v172
	v_mul_f32_e32 v66, v66, v172
	v_mul_f32_e32 v67, v67, v172
	v_mul_f32_e32 v68, v68, v172
	v_mul_f32_e32 v69, v69, v172
	v_mul_f32_e32 v70, v70, v172
	v_mul_f32_e32 v71, v71, v172
	v_mul_f32_e32 v72, v72, v172
	v_mul_f32_e32 v73, v73, v172
	v_mul_f32_e32 v74, v74, v172
	v_mul_f32_e32 v75, v75, v172
	v_mul_f32_e32 v76, v76, v172
	v_mul_f32_e32 v77, v77, v172
	v_mul_f32_e32 v78, v78, v172
	v_mul_f32_e32 v79, v79, v172
.Lat_nors_27:
	v_sub_f32_e32 v96, v96, v251
	v_sub_f32_e32 v97, v97, v251
	v_sub_f32_e32 v98, v98, v251
	v_sub_f32_e32 v99, v99, v251
	v_sub_f32_e32 v100, v100, v251
	v_sub_f32_e32 v101, v101, v251
	v_sub_f32_e32 v102, v102, v251
	v_sub_f32_e32 v103, v103, v251
	v_sub_f32_e32 v104, v104, v251
	v_sub_f32_e32 v105, v105, v251
	v_sub_f32_e32 v106, v106, v251
	v_sub_f32_e32 v107, v107, v251
	v_sub_f32_e32 v108, v108, v251
	v_sub_f32_e32 v109, v109, v251
	v_sub_f32_e32 v110, v110, v251
	v_sub_f32_e32 v111, v111, v251
	v_exp_f32_e32 v96, v96
	v_exp_f32_e32 v97, v97
	v_exp_f32_e32 v98, v98
	v_exp_f32_e32 v99, v99
	v_exp_f32_e32 v100, v100
	v_exp_f32_e32 v101, v101
	v_exp_f32_e32 v102, v102
	v_exp_f32_e32 v103, v103
	v_exp_f32_e32 v104, v104
	v_exp_f32_e32 v105, v105
	v_exp_f32_e32 v106, v106
	v_exp_f32_e32 v107, v107
	v_exp_f32_e32 v108, v108
	v_exp_f32_e32 v109, v109
	v_exp_f32_e32 v110, v110
	v_exp_f32_e32 v111, v111
	v_add_f32_e32 v212, v96, v97
	v_add_f32_e32 v250, v98, v99
	v_add_f32_e32 v212, v212, v100
	v_add_f32_e32 v250, v250, v101
	v_add_f32_e32 v212, v212, v102
	v_add_f32_e32 v250, v250, v103
	v_add_f32_e32 v212, v212, v104
	v_add_f32_e32 v250, v250, v105
	v_add_f32_e32 v212, v212, v106
	v_add_f32_e32 v250, v250, v107
	v_add_f32_e32 v212, v212, v108
	v_add_f32_e32 v250, v250, v109
	v_add_f32_e32 v212, v212, v110
	v_add_f32_e32 v250, v250, v111
	v_add_f32_e32 v212, v212, v250
	v_add_f32_e32 v3, v3, v212
	v_cvt_pk_bf16_f32 v96, v96, v97
	v_cvt_pk_bf16_f32 v97, v98, v99
	v_cvt_pk_bf16_f32 v98, v100, v101
	v_cvt_pk_bf16_f32 v99, v102, v103
	v_cvt_pk_bf16_f32 v100, v104, v105
	v_cvt_pk_bf16_f32 v101, v106, v107
	v_cvt_pk_bf16_f32 v102, v108, v109
	v_cvt_pk_bf16_f32 v103, v110, v111
	s_waitcnt lgkmcnt(4)
	v_mfma_f32_32x32x16_bf16 v[48:63], v[176:179], v[96:99], v[48:63]
	v_mfma_f32_32x32x16_bf16 v[64:79], v[184:187], v[96:99], v[64:79]
	v_mfma_f32_32x32x16_bf16 v[48:63], v[180:183], v[100:103], v[48:63]
	v_mfma_f32_32x32x16_bf16 v[64:79], v[188:191], v[100:103], v[64:79]
	ds_read_b64_tr_b16 v[176:177], v217 offset:0
	ds_read_b64_tr_b16 v[178:179], v217 offset:1152
	ds_read_b64_tr_b16 v[180:181], v217 offset:2304
	ds_read_b64_tr_b16 v[182:183], v217 offset:3456
	ds_read_b64_tr_b16 v[184:185], v217 offset:64
	ds_read_b64_tr_b16 v[186:187], v217 offset:1216
	ds_read_b64_tr_b16 v[188:189], v217 offset:2368
	ds_read_b64_tr_b16 v[190:191], v217 offset:3520
.Lat_jnext_13:
	s_mov_b32 s69, s84
	s_add_u32 s57, s57, 1
	s_cmp_lt_u32 s57, s68
	s_cbranch_scc1 .Lat_jloop_12
	s_waitcnt lgkmcnt(0)
	s_nop 7
	s_nop 7
	v_mov_b32_e32 v212, v6
	v_mov_b32_e32 v172, v6
	s_nop 1
	v_permlane32_swap_b32_e32 v212, v172
	v_add_f32_e32 v172, v212, v172
	v_rcp_f32_e32 v172, v172
	s_nop 0
	v_mul_f32_e32 v16, v16, v172
	v_mul_f32_e32 v17, v17, v172
	v_mul_f32_e32 v18, v18, v172
	v_mul_f32_e32 v19, v19, v172
	v_mul_f32_e32 v20, v20, v172
	v_mul_f32_e32 v21, v21, v172
	v_mul_f32_e32 v22, v22, v172
	v_mul_f32_e32 v23, v23, v172
	v_mul_f32_e32 v24, v24, v172
	v_mul_f32_e32 v25, v25, v172
	v_mul_f32_e32 v26, v26, v172
	v_mul_f32_e32 v27, v27, v172
	v_mul_f32_e32 v28, v28, v172
	v_mul_f32_e32 v29, v29, v172
	v_mul_f32_e32 v30, v30, v172
	v_mul_f32_e32 v31, v31, v172
	v_mul_f32_e32 v32, v32, v172
	v_mul_f32_e32 v33, v33, v172
	v_mul_f32_e32 v34, v34, v172
	v_mul_f32_e32 v35, v35, v172
	v_mul_f32_e32 v36, v36, v172
	v_mul_f32_e32 v37, v37, v172
	v_mul_f32_e32 v38, v38, v172
	v_mul_f32_e32 v39, v39, v172
	v_mul_f32_e32 v40, v40, v172
	v_mul_f32_e32 v41, v41, v172
	v_mul_f32_e32 v42, v42, v172
	v_mul_f32_e32 v43, v43, v172
	v_mul_f32_e32 v44, v44, v172
	v_mul_f32_e32 v45, v45, v172
	v_mul_f32_e32 v46, v46, v172
	v_mul_f32_e32 v47, v47, v172
	v_cvt_pk_bf16_f32 v80, v16, v17
	v_cvt_pk_bf16_f32 v81, v18, v19
	v_cvt_pk_bf16_f32 v82, v20, v21
	v_cvt_pk_bf16_f32 v83, v22, v23
	s_nop 1
	v_permlane32_swap_b32_e32 v80, v82
	v_permlane32_swap_b32_e32 v81, v83
	global_store_dwordx4 v13, v[80:83], s[44:45] offset:0
	v_cvt_pk_bf16_f32 v84, v24, v25
	v_cvt_pk_bf16_f32 v85, v26, v27
	v_cvt_pk_bf16_f32 v86, v28, v29
	v_cvt_pk_bf16_f32 v87, v30, v31
	s_nop 1
	v_permlane32_swap_b32_e32 v84, v86
	v_permlane32_swap_b32_e32 v85, v87
	global_store_dwordx4 v13, v[84:87], s[44:45] offset:32
	v_cvt_pk_bf16_f32 v80, v32, v33
	v_cvt_pk_bf16_f32 v81, v34, v35
	v_cvt_pk_bf16_f32 v82, v36, v37
	v_cvt_pk_bf16_f32 v83, v38, v39
	s_nop 1
	v_permlane32_swap_b32_e32 v80, v82
	v_permlane32_swap_b32_e32 v81, v83
	global_store_dwordx4 v13, v[80:83], s[44:45] offset:64
	v_cvt_pk_bf16_f32 v84, v40, v41
	v_cvt_pk_bf16_f32 v85, v42, v43
	v_cvt_pk_bf16_f32 v86, v44, v45
	v_cvt_pk_bf16_f32 v87, v46, v47
	s_nop 1
	v_permlane32_swap_b32_e32 v84, v86
	v_permlane32_swap_b32_e32 v85, v87
	global_store_dwordx4 v13, v[84:87], s[44:45] offset:96
	v_mov_b32_e32 v212, v3
	v_mov_b32_e32 v172, v3
	s_nop 1
	v_permlane32_swap_b32_e32 v212, v172
	v_add_f32_e32 v172, v212, v172
	v_rcp_f32_e32 v172, v172
	s_nop 0
	v_mul_f32_e32 v48, v48, v172
	v_mul_f32_e32 v49, v49, v172
	v_mul_f32_e32 v50, v50, v172
	v_mul_f32_e32 v51, v51, v172
	v_mul_f32_e32 v52, v52, v172
	v_mul_f32_e32 v53, v53, v172
	v_mul_f32_e32 v54, v54, v172
	v_mul_f32_e32 v55, v55, v172
	v_mul_f32_e32 v56, v56, v172
	v_mul_f32_e32 v57, v57, v172
	v_mul_f32_e32 v58, v58, v172
	v_mul_f32_e32 v59, v59, v172
	v_mul_f32_e32 v60, v60, v172
	v_mul_f32_e32 v61, v61, v172
	v_mul_f32_e32 v62, v62, v172
	v_mul_f32_e32 v63, v63, v172
	v_mul_f32_e32 v64, v64, v172
	v_mul_f32_e32 v65, v65, v172
	v_mul_f32_e32 v66, v66, v172
	v_mul_f32_e32 v67, v67, v172
	v_mul_f32_e32 v68, v68, v172
	v_mul_f32_e32 v69, v69, v172
	v_mul_f32_e32 v70, v70, v172
	v_mul_f32_e32 v71, v71, v172
	v_mul_f32_e32 v72, v72, v172
	v_mul_f32_e32 v73, v73, v172
	v_mul_f32_e32 v74, v74, v172
	v_mul_f32_e32 v75, v75, v172
	v_mul_f32_e32 v76, v76, v172
	v_mul_f32_e32 v77, v77, v172
	v_mul_f32_e32 v78, v78, v172
	v_mul_f32_e32 v79, v79, v172
	v_cvt_pk_bf16_f32 v80, v48, v49
	v_cvt_pk_bf16_f32 v81, v50, v51
	v_cvt_pk_bf16_f32 v82, v52, v53
	v_cvt_pk_bf16_f32 v83, v54, v55
	s_nop 1
	v_permlane32_swap_b32_e32 v80, v82
	v_permlane32_swap_b32_e32 v81, v83
	global_store_dwordx4 v14, v[80:83], s[44:45] offset:0
	v_cvt_pk_bf16_f32 v84, v56, v57
	v_cvt_pk_bf16_f32 v85, v58, v59
	v_cvt_pk_bf16_f32 v86, v60, v61
	v_cvt_pk_bf16_f32 v87, v62, v63
	s_nop 1
	v_permlane32_swap_b32_e32 v84, v86
	v_permlane32_swap_b32_e32 v85, v87
	global_store_dwordx4 v14, v[84:87], s[44:45] offset:32
	v_cvt_pk_bf16_f32 v80, v64, v65
	v_cvt_pk_bf16_f32 v81, v66, v67
	v_cvt_pk_bf16_f32 v82, v68, v69
	v_cvt_pk_bf16_f32 v83, v70, v71
	s_nop 1
	v_permlane32_swap_b32_e32 v80, v82
	v_permlane32_swap_b32_e32 v81, v83
	global_store_dwordx4 v14, v[80:83], s[44:45] offset:64
	v_cvt_pk_bf16_f32 v84, v72, v73
	v_cvt_pk_bf16_f32 v85, v74, v75
	v_cvt_pk_bf16_f32 v86, v76, v77
	v_cvt_pk_bf16_f32 v87, v78, v79
	s_nop 1
	v_permlane32_swap_b32_e32 v84, v86
	v_permlane32_swap_b32_e32 v85, v87
	global_store_dwordx4 v14, v[84:87], s[44:45] offset:96
	s_add_u32 s58, s58, 1
	s_add_u32 s53, s53, 1
	s_cmp_lt_u32 s58, 4
	s_cbranch_scc1 .Lat_unit
	s_add_u32 s52, s52, s59
	s_cmpk_lt_i32 s52, 0x100
	s_cbranch_scc1 .Lat_chunk
